# GEMM3 epilogue: merge-point vmcnt waits moved into the sample-tile-only blocks; RG-LRU pass: next-unit prefetch and chunk-state load no longer fenced by vmcnt(0) on prompt units
# speedup vs baseline: 1.0041x; 1.0041x over previous
; __device__ __forceinline__ unsigned cvt_pk_bf16(float lo, float hi) { unsigned r; asm volatile("v_cvt_pk_bf16_f32 %0, %1, %2" : "=v"(r) : "v"(lo), "v"(hi)); return r; }
; #define LAS __attribute__((address_space(3)))
; template <int MODE>
; __device__ __forceinline__ void rnn_phase(const RnnP& P, LAS unsigned char* lds, int G, int bid, int nunits) {
;     ...
;         float Hpre = 0.f; if (MODE == 1 && !samp) Hpre = P.HIN[(size_t)c * 2048 + chg];
; #pragma unroll
;         for (int k = 0; k < 3; ++k) { const int i = tid + k * NTHR; if (i < 67 * 16) { const int j = i >> 4, cc = i & 15; const v4u v = pre.x[k]; f32x4 a, b;
;             a.x = __builtin_bit_cast(float, v.x << 16); a.y = __builtin_bit_cast(float, v.x & 0xffff0000u); a.z = __builtin_bit_cast(float, v.y << 16); a.w = __builtin_bit_cast(float, v.y & 0xffff0000u);
;             b.x = __builtin_bit_cast(float, v.z << 16); b.y = __builtin_bit_cast(float, v.z & 0xffff0000u); b.z = __builtin_bit_cast(float, v.w << 16); b.w = __builtin_bit_cast(float, v.w & 0xffff0000u);
;             *(LAS f32x4*)(XRF + j * 128 + cc * 8) = a; *(LAS f32x4*)(XRF + j * 128 + cc * 8 + 4) = b; } }
;         if (MODE == 1) {
; #pragma unroll
;             for (int k = 0; k < 2; ++k) { const int i = tid + k * NTHR, j = i >> 4, cc = i & 15; *(LAS v4u*)(YGS + j * 128 + cc * 8) = pre.y[k]; } }
;         const int un = u + G; const bool has_next = un < nunits;
;         int R0n = R0, nn = n, sampn = samp, cn = c;
;         if (has_next) { rnn_decode<MODE>(un, R0n, nn, sampn, cn); rnn_issue<MODE>(P, pre, tid, R0n, nn, sampn, cn); }
;         __syncthreads();
;         float xc[16];
;         { float x3, x2, x1;
;           if (samp) { const float* sc = P.st_conv + (size_t)((R0 >> 4) + rg) * 3 * 2048 + chg; x3 = sc[0]; x2 = sc[2048]; x1 = sc[4096]; }
;           else { x3 = XRF[(16 * rg + 0) * 128 + ch]; x2 = XRF[(16 * rg + 1) * 128 + ch]; x1 = XRF[(16 * rg + 2) * 128 + ch]; }
; #pragma unroll
;           for (int i = 0; i < 16; ++i) { const float x0 = XRF[(16 * rg + 3 + i) * 128 + ch]; xc[i] = __builtin_fmaf(w3, x0, __builtin_fmaf(w2, x1, __builtin_fmaf(w1, x2, __builtin_fmaf(w0, x3, bc)))); x3 = x2; x2 = x1; x1 = x0;
;               XCB[(16 * rg + i) * 136 + ch] = (bf16)pg8::cvt_pk_bf16(xc[i], xc[i]); } }
.LBB0_2324:
	v_cndmask_b32_e64 v1, 0, 1, s[44:45]
	v_cmp_ne_u32_e64 s[40:41], 1, v1
	s_andn2_b64 vcc, exec, s[44:45]
	s_mov_b64 s[44:45], -1
	s_waitcnt lgkmcnt(0)
	s_barrier
	s_cbranch_vccnz .LBB0_2326
	s_ashr_i32 s44, s0, 4
	v_add_u32_e32 v1, s44, v124
	v_lshl_add_u32 v70, v1, 1, v1
	v_ashrrev_i32_e32 v71, 31, v70
	v_lshlrev_b64 v[70:71], 13, v[70:71]
	v_lshl_add_u64 v[70:71], s[50:51], 0, v[70:71]
	v_mov_b32_e32 v65, v10
	v_lshl_add_u64 v[72:73], v[64:65], 2, v[70:71]
	v_add_co_u32_e32 v74, vcc, 0x2000, v72
	global_load_dword v70, v[72:73], off
	s_nop 0
	v_addc_co_u32_e32 v75, vcc, 0, v73, vcc
	global_load_dword v71, v[74:75], off
	v_add_co_u32_e32 v72, vcc, 0x4000, v72
	s_mov_b64 s[44:45], 0
	s_nop 0
	v_addc_co_u32_e32 v73, vcc, 0, v73, vcc
	global_load_dword v11, v[72:73], off
	s_waitcnt vmcnt(0)
.LBB0_2326:
	s_andn2_b64 vcc, exec, s[44:45]
	s_cbranch_vccnz .LBB0_2328
	s_lshl_b32 s100, s70, 13
	s_add_u32 s100, s1, s100
	s_addc_u32 s101, s57, 0
	v_mov_b32_e32 v65, v10
	v_lshl_add_u64 v[70:71], v[64:65], 2, s[100:101]
	global_load_dword v63, v[70:71], off
	ds_read2st64_b32 v[70:71], v162 offset1:2
	ds_read_b32 v11, v162 offset:1024
.LBB0_2328:
	ds_read_b32 v1, v162 offset:1536
	s_waitcnt lgkmcnt(2)
	v_fma_f32 v78, v168, v70, v164
	v_fmac_f32_e32 v78, v167, v71
	s_waitcnt lgkmcnt(1)
	v_fmac_f32_e32 v78, v166, v11
	v_fma_f32 v79, v168, v71, v164
	s_waitcnt lgkmcnt(0)
	v_fmac_f32_e32 v78, v165, v1
	v_cvt_pk_bf16_f32 v57, v78, v78
	ds_read_b32 v65, v162 offset:2048
	v_fmac_f32_e32 v79, v167, v11
	v_fmac_f32_e32 v79, v166, v1
	ds_write_b16 v151, v57 offset:50688
	v_fma_f32 v86, v168, v11, v164
	s_waitcnt lgkmcnt(1)
	v_fmac_f32_e32 v79, v165, v65
	v_cvt_pk_bf16_f32 v57, v79, v79
	ds_read_b32 v70, v162 offset:2560
	v_fmac_f32_e32 v86, v167, v1
	v_fmac_f32_e32 v86, v166, v65
	ds_write_b16 v151, v57 offset:50960
	v_fma_f32 v87, v168, v1, v164
	s_waitcnt lgkmcnt(1)
	v_fmac_f32_e32 v86, v165, v70
	v_cvt_pk_bf16_f32 v11, v86, v86
	ds_read_b32 v57, v162 offset:3072
	v_fmac_f32_e32 v87, v167, v65
	v_fmac_f32_e32 v87, v166, v70
	ds_write_b16 v152, v11 offset:50688
	v_fma_f32 v84, v168, v65, v164
	s_waitcnt lgkmcnt(1)
	v_fmac_f32_e32 v87, v165, v57
	v_cvt_pk_bf16_f32 v1, v87, v87
	ds_read_b32 v11, v162 offset:3584
	v_fmac_f32_e32 v84, v167, v70
	v_fmac_f32_e32 v84, v166, v57
	ds_write_b16 v151, v1 offset:51504
	v_fma_f32 v85, v168, v70, v164
	s_waitcnt lgkmcnt(1)
	v_fmac_f32_e32 v84, v165, v11
	v_cvt_pk_bf16_f32 v1, v84, v84
	ds_read_b32 v65, v162 offset:4096
	v_fmac_f32_e32 v85, v167, v57
	v_fmac_f32_e32 v85, v166, v11
	ds_write_b16 v152, v1 offset:51232
	v_fma_f32 v82, v168, v57, v164
	s_waitcnt lgkmcnt(1)
	v_fmac_f32_e32 v85, v165, v65
	v_cvt_pk_bf16_f32 v1, v85, v85
	ds_read_b32 v70, v162 offset:4608
	v_fmac_f32_e32 v82, v167, v11
	v_fmac_f32_e32 v82, v166, v65
	ds_write_b16 v151, v1 offset:52048
	v_fma_f32 v83, v168, v11, v164
	s_waitcnt lgkmcnt(1)
	v_fmac_f32_e32 v82, v165, v70
	v_cvt_pk_bf16_f32 v1, v82, v82
	ds_read_b32 v57, v162 offset:5120
	v_fmac_f32_e32 v83, v167, v65
	v_fmac_f32_e32 v83, v166, v70
	ds_write_b16 v152, v1 offset:51776
	v_fma_f32 v80, v168, v65, v164
	s_waitcnt lgkmcnt(1)
	v_fmac_f32_e32 v83, v165, v57
	v_cvt_pk_bf16_f32 v1, v83, v83
	ds_read_b32 v11, v162 offset:5632
	v_fmac_f32_e32 v80, v167, v70
	v_fmac_f32_e32 v80, v166, v57
	ds_write_b16 v151, v1 offset:52592
	v_fma_f32 v81, v168, v70, v164
	s_waitcnt lgkmcnt(1)
	v_fmac_f32_e32 v80, v165, v11
	v_cvt_pk_bf16_f32 v1, v80, v80
	ds_read_b32 v65, v162 offset:6144
	v_fmac_f32_e32 v81, v167, v57
	v_fmac_f32_e32 v81, v166, v11
	ds_write_b16 v152, v1 offset:52320
	v_fma_f32 v76, v168, v57, v164
	s_waitcnt lgkmcnt(1)
	v_fmac_f32_e32 v81, v165, v65
	v_cvt_pk_bf16_f32 v1, v81, v81
	ds_read_b32 v70, v162 offset:6656
	v_fmac_f32_e32 v76, v167, v11
	v_fmac_f32_e32 v76, v166, v65
	ds_write_b16 v151, v1 offset:53136
	v_fma_f32 v77, v168, v11, v164
	s_waitcnt lgkmcnt(1)
	v_fmac_f32_e32 v76, v165, v70
	v_cvt_pk_bf16_f32 v1, v76, v76
	ds_read_b32 v57, v162 offset:7168
	v_fmac_f32_e32 v77, v167, v65
	v_fmac_f32_e32 v77, v166, v70
	ds_write_b16 v152, v1 offset:52864
	v_fma_f32 v74, v168, v65, v164
	s_waitcnt lgkmcnt(1)
	v_fmac_f32_e32 v77, v165, v57
	v_cvt_pk_bf16_f32 v1, v77, v77
	ds_read_b32 v11, v162 offset:7680
	v_fmac_f32_e32 v74, v167, v70
	v_fmac_f32_e32 v74, v166, v57
	ds_write_b16 v151, v1 offset:53680
	v_fma_f32 v75, v168, v70, v164
	s_waitcnt lgkmcnt(1)
	v_fmac_f32_e32 v74, v165, v11
	v_cvt_pk_bf16_f32 v1, v74, v74
	ds_read_b32 v65, v162 offset:8192
	v_fmac_f32_e32 v75, v167, v57
	v_fmac_f32_e32 v75, v166, v11
	ds_write_b16 v152, v1 offset:53408
	v_fma_f32 v72, v168, v57, v164
	s_waitcnt lgkmcnt(1)
	v_fmac_f32_e32 v75, v165, v65
	v_cvt_pk_bf16_f32 v1, v75, v75
	ds_read_b32 v70, v162 offset:8704
	v_fmac_f32_e32 v72, v167, v11
	v_fmac_f32_e32 v72, v166, v65
	ds_write_b16 v151, v1 offset:54224
	v_fma_f32 v73, v168, v11, v164
	s_waitcnt lgkmcnt(1)
	v_fmac_f32_e32 v72, v165, v70
	v_cvt_pk_bf16_f32 v1, v72, v72
	ds_read_b32 v57, v162 offset:9216
	v_fmac_f32_e32 v73, v167, v65
	v_fmac_f32_e32 v73, v166, v70
	ds_write_b16 v152, v1 offset:53952
	s_and_b64 vcc, exec, s[40:41]
	s_waitcnt lgkmcnt(1)
	v_fmac_f32_e32 v73, v165, v57
	v_cvt_pk_bf16_f32 v1, v73, v73
	ds_write_b16 v151, v1 offset:54768
	s_waitcnt lgkmcnt(0)
	s_barrier
; #define LAS __attribute__((address_space(3)))
; template <int MODE>
; __device__ __forceinline__ void rnn_phase(const RnnP& P, LAS unsigned char* lds, int G, int bid, int nunits) {
;     ...
; #pragma unroll
;         for (int mt = 0; mt < 4; ++mt) { f32x4 d0 = (f32x4){0.f, 0.f, 0.f, 0.f}, d1 = d0;
; #pragma unroll
;             for (int kk = 0; kk < 4; ++kk) { const bf16x8 a = *(const LAS bf16x8*)(XCB + (16 * mt + jj) * 136 + 32 * kk + 8 * q);
;                 d0 = __builtin_amdgcn_mfma_f32_16x16x32_bf16(a, Bf[0][kk], d0, 0, 0, 0); d1 = __builtin_amdgcn_mfma_f32_16x16x32_bf16(a, Bf[1][kk], d1, 0, 0, 0); }
; #pragma unroll
;             for (int ep = 0; ep < 2; ++ep) { const int row = 16 * mt + 4 * q + 2 * ep;
;                 const f32x2 t0 = (f32x2){d0[2 * ep], d0[2 * ep + 1]} * (f32x2){-1.4426950408889634f, -1.4426950408889634f} + (f32x2){nb0, nb0};
;                 const f32x2 t1 = (f32x2){d1[2 * ep], d1[2 * ep + 1]} * (f32x2){-1.4426950408889634f, -1.4426950408889634f} + (f32x2){nb1, nb1};
;                 const f32x2 e0 = (f32x2){__builtin_amdgcn_exp2f(t0.x), __builtin_amdgcn_exp2f(t0.y)} + (f32x2){1.f, 1.f}, e1 = (f32x2){__builtin_amdgcn_exp2f(t1.x), __builtin_amdgcn_exp2f(t1.y)} + (f32x2){1.f, 1.f};
;                 GT[(gate * 64 + row) * GTP + cb + jj] = __builtin_amdgcn_rcpf(e0.x); GT[(gate * 64 + row + 1) * GTP + cb + jj] = __builtin_amdgcn_rcpf(e0.y);
;                 GT[(gate * 64 + row) * GTP + cb + 16 + jj] = __builtin_amdgcn_rcpf(e1.x); GT[(gate * 64 + row + 1) * GTP + cb + 16 + jj] = __builtin_amdgcn_rcpf(e1.y); } }
	ds_read_b128 v[88:91], v153 offset:50688
	ds_read_b128 v[92:95], v153 offset:50752
	s_waitcnt lgkmcnt(1)
	v_mfma_f32_16x16x32_bf16 v[96:99], v[88:91], v[24:27], 0
	s_mov_b64 s[44:45], -1
	v_mfma_f32_16x16x32_bf16 v[88:91], v[88:91], v[40:43], 0
	s_waitcnt lgkmcnt(0)
	v_mfma_f32_16x16x32_bf16 v[96:99], v[92:95], v[28:31], v[96:99]
	v_mfma_f32_16x16x32_bf16 v[88:91], v[92:95], v[44:47], v[88:91]
	ds_read_b128 v[92:95], v153 offset:50816
	ds_read_b128 v[100:103], v153 offset:50880
	s_waitcnt lgkmcnt(1)
	v_mfma_f32_16x16x32_bf16 v[96:99], v[92:95], v[32:35], v[96:99]
	v_mfma_f32_16x16x32_bf16 v[88:91], v[92:95], v[48:51], v[88:91]
	s_waitcnt lgkmcnt(0)
	v_mfma_f32_16x16x32_bf16 v[92:95], v[100:103], v[36:39], v[96:99]
	v_mfma_f32_16x16x32_bf16 v[88:91], v[100:103], v[52:55], v[88:91]
	s_nop 6
	v_fma_f32 v70, -v92, s84, v66
	v_fma_f32 v71, -v93, s84, v66
	v_pk_fma_f32 v[88:89], v[88:89], s[84:85], v[68:69] op_sel:[0,0,1] op_sel_hi:[1,0,1] neg_lo:[1,0,0] neg_hi:[1,0,0]
	v_exp_f32_e32 v70, v70
	v_exp_f32_e32 v71, v71
	v_exp_f32_e32 v88, v88
	v_exp_f32_e32 v89, v89
	v_pk_fma_f32 v[90:91], v[90:91], s[84:85], v[68:69] op_sel:[0,0,1] op_sel_hi:[1,0,1] neg_lo:[1,0,0] neg_hi:[1,0,0]
	v_pk_add_f32 v[70:71], v[70:71], 1.0 op_sel_hi:[1,0]
	v_exp_f32_e32 v90, v90
	v_pk_add_f32 v[88:89], v[88:89], 1.0 op_sel_hi:[1,0]
	v_rcp_f32_e32 v1, v70
	v_rcp_f32_e32 v11, v71
	v_pk_fma_f32 v[70:71], v[94:95], s[84:85], v[66:67] op_sel_hi:[1,0,0] neg_lo:[1,0,0] neg_hi:[1,0,0]
	v_rcp_f32_e32 v57, v88
	v_exp_f32_e32 v70, v70
	v_exp_f32_e32 v71, v71
	v_exp_f32_e32 v91, v91
	ds_write2_b32 v133, v1, v57 offset1:16
	v_rcp_f32_e32 v1, v89
	v_pk_add_f32 v[70:71], v[70:71], 1.0 op_sel_hi:[1,0]
	v_pk_add_f32 v[88:89], v[90:91], 1.0 op_sel_hi:[1,0]
	v_rcp_f32_e32 v57, v70
	v_rcp_f32_e32 v70, v88
	v_rcp_f32_e32 v65, v71
	v_rcp_f32_e32 v71, v89
	ds_write2_b32 v133, v11, v1 offset0:132 offset1:148
	v_add_u32_e32 v1, 0x400, v133
	ds_write2_b32 v1, v57, v70 offset0:8 offset1:24
	ds_write2_b32 v134, v65, v71 offset0:132 offset1:148
	ds_read_b128 v[88:91], v153 offset:55040
	ds_read_b128 v[92:95], v153 offset:55104
	s_waitcnt lgkmcnt(1)
	v_mfma_f32_16x16x32_bf16 v[96:99], v[88:91], v[24:27], 0
	v_add_u32_e32 v65, 0x2000, v133
	v_mfma_f32_16x16x32_bf16 v[88:91], v[88:91], v[40:43], 0
	s_waitcnt lgkmcnt(0)
	v_mfma_f32_16x16x32_bf16 v[96:99], v[92:95], v[28:31], v[96:99]
	v_mfma_f32_16x16x32_bf16 v[88:91], v[92:95], v[44:47], v[88:91]
	ds_read_b128 v[92:95], v153 offset:55168
	ds_read_b128 v[100:103], v153 offset:55232
	s_waitcnt lgkmcnt(1)
	v_mfma_f32_16x16x32_bf16 v[96:99], v[92:95], v[32:35], v[96:99]
	v_mfma_f32_16x16x32_bf16 v[88:91], v[92:95], v[48:51], v[88:91]
	s_waitcnt lgkmcnt(0)
	v_mfma_f32_16x16x32_bf16 v[92:95], v[100:103], v[36:39], v[96:99]
	v_mfma_f32_16x16x32_bf16 v[88:91], v[100:103], v[52:55], v[88:91]
	s_nop 6
	v_fma_f32 v70, -v92, s84, v66
	v_fma_f32 v71, -v93, s84, v66
	v_pk_fma_f32 v[88:89], v[88:89], s[84:85], v[68:69] op_sel:[0,0,1] op_sel_hi:[1,0,1] neg_lo:[1,0,0] neg_hi:[1,0,0]
	v_exp_f32_e32 v70, v70
	v_exp_f32_e32 v71, v71
	v_exp_f32_e32 v88, v88
	v_exp_f32_e32 v89, v89
	v_pk_fma_f32 v[90:91], v[90:91], s[84:85], v[68:69] op_sel:[0,0,1] op_sel_hi:[1,0,1] neg_lo:[1,0,0] neg_hi:[1,0,0]
	v_pk_add_f32 v[70:71], v[70:71], 1.0 op_sel_hi:[1,0]
	v_exp_f32_e32 v90, v90
	v_pk_add_f32 v[88:89], v[88:89], 1.0 op_sel_hi:[1,0]
	v_rcp_f32_e32 v1, v70
	v_rcp_f32_e32 v11, v71
	v_pk_fma_f32 v[70:71], v[94:95], s[84:85], v[66:67] op_sel_hi:[1,0,0] neg_lo:[1,0,0] neg_hi:[1,0,0]
	v_rcp_f32_e32 v57, v88
	v_exp_f32_e32 v70, v70
	v_exp_f32_e32 v71, v71
	v_exp_f32_e32 v91, v91
	ds_write2_b32 v65, v1, v57 offset0:64 offset1:80
	v_rcp_f32_e32 v1, v89
	v_pk_add_f32 v[70:71], v[70:71], 1.0 op_sel_hi:[1,0]
	v_pk_add_f32 v[88:89], v[90:91], 1.0 op_sel_hi:[1,0]
	v_rcp_f32_e32 v57, v70
	v_rcp_f32_e32 v70, v88
	v_rcp_f32_e32 v65, v71
	v_rcp_f32_e32 v71, v89
	ds_write2_b32 v135, v11, v1 offset0:132 offset1:148
	v_add_u32_e32 v1, 0x2400, v133
	ds_write2_b32 v1, v57, v70 offset0:72 offset1:88
	ds_write2_b32 v136, v65, v71 offset0:132 offset1:148
	ds_read_b128 v[88:91], v153 offset:59392
	ds_read_b128 v[92:95], v153 offset:59456
	s_waitcnt lgkmcnt(1)
	v_mfma_f32_16x16x32_bf16 v[96:99], v[88:91], v[24:27], 0
	v_add_u32_e32 v65, 0x4000, v133
	v_mfma_f32_16x16x32_bf16 v[88:91], v[88:91], v[40:43], 0
	s_waitcnt lgkmcnt(0)
	v_mfma_f32_16x16x32_bf16 v[96:99], v[92:95], v[28:31], v[96:99]
	v_mfma_f32_16x16x32_bf16 v[88:91], v[92:95], v[44:47], v[88:91]
	ds_read_b128 v[92:95], v153 offset:59520
	ds_read_b128 v[100:103], v153 offset:59584
	s_waitcnt lgkmcnt(1)
	v_mfma_f32_16x16x32_bf16 v[96:99], v[92:95], v[32:35], v[96:99]
	v_mfma_f32_16x16x32_bf16 v[88:91], v[92:95], v[48:51], v[88:91]
	s_waitcnt lgkmcnt(0)
; #define LAS __attribute__((address_space(3)))
; template <int MODE>
; __device__ __forceinline__ void rnn_phase(const RnnP& P, LAS unsigned char* lds, int G, int bid, int nunits) {
;     ...
; #pragma unroll
;         for (int mt = 0; mt < 4; ++mt) { f32x4 d0 = (f32x4){0.f, 0.f, 0.f, 0.f}, d1 = d0;
; #pragma unroll
;             for (int kk = 0; kk < 4; ++kk) { const bf16x8 a = *(const LAS bf16x8*)(XCB + (16 * mt + jj) * 136 + 32 * kk + 8 * q);
;                 d0 = __builtin_amdgcn_mfma_f32_16x16x32_bf16(a, Bf[0][kk], d0, 0, 0, 0); d1 = __builtin_amdgcn_mfma_f32_16x16x32_bf16(a, Bf[1][kk], d1, 0, 0, 0); }
; #pragma unroll
;             for (int ep = 0; ep < 2; ++ep) { const int row = 16 * mt + 4 * q + 2 * ep;
;                 const f32x2 t0 = (f32x2){d0[2 * ep], d0[2 * ep + 1]} * (f32x2){-1.4426950408889634f, -1.4426950408889634f} + (f32x2){nb0, nb0};
;                 const f32x2 t1 = (f32x2){d1[2 * ep], d1[2 * ep + 1]} * (f32x2){-1.4426950408889634f, -1.4426950408889634f} + (f32x2){nb1, nb1};
;                 const f32x2 e0 = (f32x2){__builtin_amdgcn_exp2f(t0.x), __builtin_amdgcn_exp2f(t0.y)} + (f32x2){1.f, 1.f}, e1 = (f32x2){__builtin_amdgcn_exp2f(t1.x), __builtin_amdgcn_exp2f(t1.y)} + (f32x2){1.f, 1.f};
;                 GT[(gate * 64 + row) * GTP + cb + jj] = __builtin_amdgcn_rcpf(e0.x); GT[(gate * 64 + row + 1) * GTP + cb + jj] = __builtin_amdgcn_rcpf(e0.y);
;                 GT[(gate * 64 + row) * GTP + cb + 16 + jj] = __builtin_amdgcn_rcpf(e1.x); GT[(gate * 64 + row + 1) * GTP + cb + 16 + jj] = __builtin_amdgcn_rcpf(e1.y); } }
;         __syncthreads();
;         float Lr[16], Pr[16];
;         { float L = 0.f, Pp = 1.f;
; #pragma unroll
;           for (int ip = 0; ip < 8; ++ip) { const int i = 2 * ip;
;               const f32x2 r2 = (f32x2){GT[(16 * rg + i) * GTP + ch], GT[(16 * rg + i + 1) * GTP + ch]}, ig2 = (f32x2){GT[(64 + 16 * rg + i) * GTP + ch], GT[(64 + 16 * rg + i + 1) * GTP + ch]};
;               const f32x2 t2 = r2 * (f32x2){c2s, c2s};
;               const f32x2 a2 = (f32x2){__builtin_amdgcn_exp2f(t2.x), __builtin_amdgcn_exp2f(t2.y)};
;               const f32x2 om2 = (f32x2){1.f, 1.f} - a2 * a2;
;               const f32x2 bt2 = (f32x2){__builtin_amdgcn_sqrtf(om2.x), __builtin_amdgcn_sqrtf(om2.y)} * (ig2 * (f32x2){xc[i], xc[i + 1]});
;               L = a2.x * L + bt2.x; Pp *= a2.x; Lr[i] = L; Pr[i] = Pp;
	v_mfma_f32_16x16x32_bf16 v[92:95], v[100:103], v[36:39], v[96:99]
	v_mfma_f32_16x16x32_bf16 v[88:91], v[100:103], v[52:55], v[88:91]
	s_nop 6
	v_fma_f32 v70, -v92, s84, v66
	v_fma_f32 v71, -v93, s84, v66
	v_pk_fma_f32 v[88:89], v[88:89], s[84:85], v[68:69] op_sel:[0,0,1] op_sel_hi:[1,0,1] neg_lo:[1,0,0] neg_hi:[1,0,0]
	v_exp_f32_e32 v70, v70
	v_exp_f32_e32 v71, v71
	v_exp_f32_e32 v88, v88
	v_exp_f32_e32 v89, v89
	v_pk_fma_f32 v[90:91], v[90:91], s[84:85], v[68:69] op_sel:[0,0,1] op_sel_hi:[1,0,1] neg_lo:[1,0,0] neg_hi:[1,0,0]
	v_pk_add_f32 v[70:71], v[70:71], 1.0 op_sel_hi:[1,0]
	v_exp_f32_e32 v90, v90
	v_pk_add_f32 v[88:89], v[88:89], 1.0 op_sel_hi:[1,0]
	v_rcp_f32_e32 v1, v70
	v_rcp_f32_e32 v11, v71
	v_pk_fma_f32 v[70:71], v[94:95], s[84:85], v[66:67] op_sel_hi:[1,0,0] neg_lo:[1,0,0] neg_hi:[1,0,0]
	v_rcp_f32_e32 v57, v88
	v_exp_f32_e32 v70, v70
	v_exp_f32_e32 v71, v71
	v_exp_f32_e32 v91, v91
	ds_write2_b32 v65, v1, v57 offset0:128 offset1:144
	v_rcp_f32_e32 v1, v89
	v_pk_add_f32 v[70:71], v[70:71], 1.0 op_sel_hi:[1,0]
	v_pk_add_f32 v[88:89], v[90:91], 1.0 op_sel_hi:[1,0]
	v_rcp_f32_e32 v57, v70
	v_rcp_f32_e32 v70, v88
	v_rcp_f32_e32 v65, v71
	v_rcp_f32_e32 v71, v89
	ds_write2_b32 v137, v11, v1 offset0:132 offset1:148
	v_add_u32_e32 v1, 0x4400, v133
	ds_write2_b32 v1, v57, v70 offset0:136 offset1:152
	ds_write2_b32 v138, v65, v71 offset0:132 offset1:148
	ds_read_b128 v[88:91], v153 offset:63744
	ds_read_b128 v[92:95], v153 offset:63808
	s_waitcnt lgkmcnt(1)
	v_mfma_f32_16x16x32_bf16 v[96:99], v[88:91], v[24:27], 0
	v_add_u32_e32 v65, 0x6000, v133
	v_mfma_f32_16x16x32_bf16 v[88:91], v[88:91], v[40:43], 0
	s_waitcnt lgkmcnt(0)
	v_mfma_f32_16x16x32_bf16 v[96:99], v[92:95], v[28:31], v[96:99]
	v_mfma_f32_16x16x32_bf16 v[88:91], v[92:95], v[44:47], v[88:91]
	ds_read_b128 v[92:95], v153 offset:63872
	ds_read_b128 v[100:103], v153 offset:63936
	s_waitcnt lgkmcnt(1)
	v_mfma_f32_16x16x32_bf16 v[96:99], v[92:95], v[32:35], v[96:99]
	v_mfma_f32_16x16x32_bf16 v[88:91], v[92:95], v[48:51], v[88:91]
	s_waitcnt lgkmcnt(0)
	v_mfma_f32_16x16x32_bf16 v[92:95], v[100:103], v[36:39], v[96:99]
	v_mfma_f32_16x16x32_bf16 v[88:91], v[100:103], v[52:55], v[88:91]
	s_nop 6
	v_fma_f32 v70, -v92, s84, v66
	v_fma_f32 v71, -v93, s84, v66
	v_pk_fma_f32 v[88:89], v[88:89], s[84:85], v[68:69] op_sel:[0,0,1] op_sel_hi:[1,0,1] neg_lo:[1,0,0] neg_hi:[1,0,0]
	v_exp_f32_e32 v70, v70
	v_exp_f32_e32 v71, v71
	v_exp_f32_e32 v88, v88
	v_exp_f32_e32 v89, v89
	v_pk_fma_f32 v[90:91], v[90:91], s[84:85], v[68:69] op_sel:[0,0,1] op_sel_hi:[1,0,1] neg_lo:[1,0,0] neg_hi:[1,0,0]
	v_pk_add_f32 v[70:71], v[70:71], 1.0 op_sel_hi:[1,0]
	v_exp_f32_e32 v90, v90
	v_pk_add_f32 v[88:89], v[88:89], 1.0 op_sel_hi:[1,0]
	v_rcp_f32_e32 v1, v70
	v_rcp_f32_e32 v11, v71
	v_pk_fma_f32 v[70:71], v[94:95], s[84:85], v[66:67] op_sel_hi:[1,0,0] neg_lo:[1,0,0] neg_hi:[1,0,0]
	v_rcp_f32_e32 v57, v88
	v_exp_f32_e32 v70, v70
	v_exp_f32_e32 v71, v71
	v_exp_f32_e32 v91, v91
	ds_write2_b32 v65, v1, v57 offset0:192 offset1:208
	v_rcp_f32_e32 v1, v89
	v_pk_add_f32 v[70:71], v[70:71], 1.0 op_sel_hi:[1,0]
	v_pk_add_f32 v[88:89], v[90:91], 1.0 op_sel_hi:[1,0]
	v_rcp_f32_e32 v57, v70
	v_rcp_f32_e32 v70, v88
	v_rcp_f32_e32 v65, v71
	v_rcp_f32_e32 v71, v89
	ds_write2_b32 v139, v11, v1 offset0:132 offset1:148
	v_add_u32_e32 v1, 0x6400, v133
	ds_write2_b32 v1, v57, v70 offset0:200 offset1:216
	ds_write2_b32 v140, v65, v71 offset0:132 offset1:148
	v_add_u32_e32 v1, 0x8400, v141
	s_waitcnt lgkmcnt(0)
	s_barrier
	ds_read2_b32 v[88:89], v141 offset1:132
	ds_read2_b32 v[102:103], v1 offset1:132
	ds_read2_b32 v[118:119], v142 offset1:132
	v_add_u32_e32 v1, 0x8800, v141
	ds_read2_b32 v[94:95], v1 offset0:8 offset1:140
	ds_read2_b32 v[100:101], v143 offset1:132
	v_add_u32_e32 v1, 0x8c00, v141
	ds_read2_b32 v[98:99], v1 offset0:16 offset1:148
	ds_read2_b32 v[96:97], v144 offset1:132
	v_add_u32_e32 v1, 0x9000, v141
	ds_read2_b32 v[116:117], v1 offset0:24 offset1:156
	ds_read2_b32 v[92:93], v145 offset1:132
	v_add_u32_e32 v1, 0x9400, v141
	ds_read2_b32 v[114:115], v1 offset0:32 offset1:164
	ds_read2_b32 v[90:91], v146 offset1:132
	v_add_u32_e32 v1, 0x9800, v141
	ds_read2_b32 v[112:113], v1 offset0:40 offset1:172
	ds_read2_b32 v[110:111], v147 offset1:132
	v_add_u32_e32 v1, 0x9c00, v141
	ds_read2_b32 v[108:109], v1 offset0:48 offset1:180
	ds_read2_b32 v[106:107], v148 offset1:132
	v_add_u32_e32 v1, 0xa000, v141
	ds_read2_b32 v[104:105], v1 offset0:56 offset1:188
	s_cbranch_vccnz .LBB0_2330
	s_ashr_i32 s44, s0, 4
	v_add_u32_e32 v70, s44, v124
	v_ashrrev_i32_e32 v71, 31, v70
	v_lshlrev_b64 v[70:71], 13, v[70:71]
	v_mov_b32_e32 v65, v10
	v_lshl_add_u64 v[70:71], s[48:49], 0, v[70:71]
	v_lshl_add_u64 v[70:71], v[64:65], 2, v[70:71]
	global_load_dword v70, v[70:71], off
	s_mov_b64 s[44:45], 0

; #define GAS __attribute__((address_space(1)))
; template <int MODE>
; __device__ __forceinline__ void rnn_phase(const RnnP& P, LAS unsigned char* lds, int G, int bid, int nunits) {
;     ...
;         const int chg = n * 128 + ch;
;         if (n != n_loaded) {
;             const bf16* WT = (gate ? P.WXT : P.WAT) + (size_t)n * 16384;
; #pragma unroll
;             for (int nt = 0; nt < 2; ++nt)
; #pragma unroll
;                 for (int kk = 0; kk < 4; ++kk) Bf[nt][kk] = *(const GAS bf16x8*)(WT + (size_t)(cb + 16 * nt + jj) * 128 + 32 * kk + 8 * q);
;             const float* bsrc = (gate ? P.b_x : P.b_a) + n * 128 + cb; nb0 = -1.4426950408889634f * bsrc[jj]; nb1 = -1.4426950408889634f * bsrc[16 + jj];
;             w0 = P.wconv[chg]; w1 = P.wconv[2048 + chg]; w2 = P.wconv[4096 + chg]; w3 = P.wconv[6144 + chg]; bc = P.bconv[chg];
;             c2s = -1.4426950408889634f * 8.f * log1pf(__expf(-P.lam[chg])); n_loaded = n; }
;         float Hpre = 0.f; if (MODE == 1 && !samp) Hpre = P.HIN[(size_t)c * 2048 + chg];
.LBB0_2348:
	s_mov_b32 s71, s67
	s_lshl_b64 s[40:41], s[70:71], 13
	s_add_u32 s40, s1, s40
	s_addc_u32 s41, s57, s41
	v_mov_b32_e32 v65, v10
	v_lshl_add_u64 v[70:71], v[64:65], 2, s[40:41]
	s_and_saveexec_b64 s[40:41], s[6:7]
	s_cbranch_execnz .LBB0_2309

;     __device__ __forceinline__ void operator()(const f32x4 (&acc)[2][2][4][2], const Unit& u, int wr, int wc, int fr, int fq) const {
;     ...
;                 if (pm == 0) {
;                     if (fr < 2) { const float* st = stf + (size_t)(row >> 4) * 2 * DFF + col0;
; #pragma unroll
;                         for (int n = 0; n < 2; ++n) { const f32x4 b0 = *(const f32x4*)(st + 4 * n), b1 = *(const f32x4*)(st + DFF + 4 * n); if (fr == 0) { z1[n] = b1; z2[n] = b0; } else { z2[n] = b1; } } }
;                     const int s16 = row & 15;
;                     if (s16 >= 14) { float* dst = o_fcs + (size_t)((row >> 4) * 2 + (s16 - 14)) * DFF + col0; *(f32x4*)dst = zc[0]; *(f32x4*)(dst + 4) = zc[1]; }
.LBB0_2669:
	s_or_b64 exec, exec, s[86:87]
	s_waitcnt vmcnt(0)
	s_and_saveexec_b64 s[86:87], s[84:85]
	s_cbranch_execnz .LBB0_2672
	s_branch .LBB0_2673

; __device__ __forceinline__ u32x4 pack8(f32x4 a, f32x4 b) { u32x4 w; w.x = cvt_pk_bf16(a[0], a[1]); w.y = cvt_pk_bf16(a[2], a[3]); w.z = cvt_pk_bf16(b[0], b[1]); w.w = cvt_pk_bf16(b[2], b[3]); return w; }
;     __device__ __forceinline__ void operator()(const f32x4 (&acc)[2][2][4][2], const Unit& u, int wr, int wc, int fr, int fq) const {
;     ...
;                 const bool defer = pm != 0 && m == 0 && fr < 2;
;                 if (!defer) { f32x4 a[2];
; #pragma unroll
;                     for (int n = 0; n < 2; ++n)
;                     { const f32x4 g = bb[n] + w0[n] * z2[n] + w1[n] * z1[n] + w2[n] * zc[n]; a[n] = gelu4(g) * vv[n]; }
;                     *(u32x4*)(ACT + (size_t)row * DFF + col0) = pack8(a[0], a[1]);
.LBB0_2673:
	s_or_b64 exec, exec, s[86:87]
	s_cmp_lg_u32 s18, 0
	s_cselect_b64 s[86:87], -1, 0
	v_mov_b32_e32 v237, v236
	v_mov_b32_e32 v14, v236
	v_mov_b32_e32 v15, v236
	s_and_b64 s[18:19], s[86:87], s[10:11]
	v_lshl_add_u64 v[216:217], v[212:213], 1, s[44:45]
	v_pk_mul_f32 v[168:169], v[168:169], v[14:15]
	v_pk_mul_f32 v[166:167], v[166:167], v[236:237]
	v_pk_mul_f32 v[16:17], v[164:165], v[14:15]
	v_pk_mul_f32 v[14:15], v[162:163], v[236:237]
	s_xor_b64 s[84:85], s[18:19], -1
	s_and_saveexec_b64 s[18:19], s[84:85]
	s_xor_b64 s[18:19], exec, s[18:19]
	s_cbranch_execz .LBB0_2675
	v_pk_fma_f32 v[162:163], v[68:69], v[180:181], v[72:73]
	v_pk_fma_f32 v[164:165], v[66:67], v[178:179], v[70:71]
	v_pk_fma_f32 v[10:11], v[50:51], v[10:11], v[54:55]
	v_pk_fma_f32 v[4:5], v[64:65], v[4:5], v[162:163]
	v_pk_fma_f32 v[2:3], v[62:63], v[2:3], v[164:165]
	v_pk_fma_f32 v[6:7], v[46:47], v[6:7], v[10:11]
	v_pk_fma_f32 v[4:5], v[60:61], v[176:177], v[4:5]
	v_pk_fma_f32 v[2:3], v[58:59], v[174:175], v[2:3]
	v_pk_fma_f32 v[12:13], v[52:53], v[12:13], v[56:57]
	v_pk_fma_f32 v[6:7], v[42:43], v[170:171], v[6:7]
	v_pk_mul_f32 v[162:163], v[4:5], v[4:5]
	v_pk_mul_f32 v[164:165], v[2:3], v[2:3]
	v_mov_b64_e32 v[178:179], s[72:73]
	v_pk_fma_f32 v[8:9], v[48:49], v[8:9], v[12:13]
	v_pk_mul_f32 v[12:13], v[6:7], v[6:7]
	v_pk_fma_f32 v[162:163], v[162:163], s[74:75], v[178:179] op_sel_hi:[1,0,0] neg_lo:[1,0,0] neg_hi:[1,0,0]
	v_pk_fma_f32 v[164:165], v[164:165], s[74:75], v[178:179] op_sel_hi:[1,0,0] neg_lo:[1,0,0] neg_hi:[1,0,0]
	v_pk_fma_f32 v[8:9], v[44:45], v[172:173], v[8:9]
	v_pk_fma_f32 v[12:13], v[12:13], s[74:75], v[178:179] op_sel_hi:[1,0,0] neg_lo:[1,0,0] neg_hi:[1,0,0]
	v_pk_mul_f32 v[162:163], v[4:5], v[162:163]
	v_pk_mul_f32 v[164:165], v[2:3], v[164:165]
	v_pk_mul_f32 v[10:11], v[8:9], v[8:9]
	v_pk_mul_f32 v[12:13], v[6:7], v[12:13]
	v_exp_f32_e32 v164, v164
	v_exp_f32_e32 v165, v165
	v_exp_f32_e32 v162, v162
	v_exp_f32_e32 v163, v163
	v_pk_fma_f32 v[10:11], v[10:11], s[74:75], v[178:179] op_sel_hi:[1,0,0] neg_lo:[1,0,0] neg_hi:[1,0,0]
	v_exp_f32_e32 v12, v12
	v_exp_f32_e32 v13, v13
	v_pk_mul_f32 v[10:11], v[8:9], v[10:11]
	v_pk_add_f32 v[162:163], v[162:163], 1.0 op_sel_hi:[1,0]
	v_exp_f32_e32 v10, v10
	v_exp_f32_e32 v11, v11
	v_pk_add_f32 v[164:165], v[164:165], 1.0 op_sel_hi:[1,0]
	v_pk_add_f32 v[12:13], v[12:13], 1.0 op_sel_hi:[1,0]
	v_rcp_f32_e32 v164, v164
	v_rcp_f32_e32 v165, v165
	v_rcp_f32_e32 v162, v162
	v_rcp_f32_e32 v163, v163
	v_rcp_f32_e32 v12, v12
	v_rcp_f32_e32 v13, v13
	v_pk_add_f32 v[10:11], v[10:11], 1.0 op_sel_hi:[1,0]
	v_pk_mul_f32 v[4:5], v[4:5], v[162:163]
	v_rcp_f32_e32 v10, v10
	v_rcp_f32_e32 v11, v11
	v_pk_mul_f32 v[2:3], v[2:3], v[164:165]
	v_pk_mul_f32 v[6:7], v[6:7], v[12:13]
	v_pk_mul_f32 v[4:5], v[168:169], v[4:5]
	v_pk_mul_f32 v[2:3], v[166:167], v[2:3]
	v_pk_mul_f32 v[6:7], v[14:15], v[6:7]
	v_pk_mul_f32 v[8:9], v[8:9], v[10:11]
	v_cvt_pk_bf16_f32 v2, v2, v3
	v_cvt_pk_bf16_f32 v3, v4, v5
	v_cvt_pk_bf16_f32 v4, v6, v7
	v_mad_i64_i32 v[6:7], s[88:89], v214, s97, v[216:217]
	v_pk_mul_f32 v[8:9], v[16:17], v[8:9]
	s_nop 0
	v_cvt_pk_bf16_f32 v5, v8, v9
	global_store_dwordx4 v[6:7], v[2:5], off

;     __device__ __forceinline__ void operator()(const f32x4 (&acc)[2][2][4][2], const Unit& u, int wr, int wc, int fr, int fq) const {
;     ...
;                 for (int n = 0; n < 2; ++n) { zc[n] = acc[ai][0][m][n] * s; vv[n] = acc[ai][1][m][n] * s; zp[n] = zprev[n]; zprev[n] = zc[n]; }
; #pragma unroll
;                 for (int n = 0; n < 2; ++n)
; #pragma unroll
;                     for (int e = 0; e < 4; ++e) { const float t1 = fr == 15 ? zp[n][e] : zc[n][e], t2 = fr >= 14 ? zp[n][e] : zc[n][e];
;                         z1[n][e] = __builtin_bit_cast(float, __builtin_amdgcn_mov_dpp(__builtin_bit_cast(int, t1), 0x121, 0xf, 0xf, true));
;                         z2[n][e] = __builtin_bit_cast(float, __builtin_amdgcn_mov_dpp(__builtin_bit_cast(int, t2), 0x122, 0xf, 0xf, true)); }
.LBB0_2677:
	s_or_b64 exec, exec, s[18:19]
	v_pk_mul_f32 v[158:159], v[158:159], v[234:235] op_sel_hi:[1,0]
	v_pk_mul_f32 v[160:161], v[160:161], v[234:235] op_sel_hi:[1,0]
	v_cndmask_b32_e64 v2, v158, v174, s[6:7]
	v_cndmask_b32_e64 v3, v158, v174, s[8:9]
	v_pk_mul_f32 v[14:15], v[154:155], v[234:235] op_sel_hi:[1,0]
	v_mov_b32_dpp v154, v2 row_ror:1 row_mask:0xf bank_mask:0xf bound_ctrl:1
	v_mov_b32_dpp v2, v3 row_ror:2 row_mask:0xf bank_mask:0xf bound_ctrl:1
	v_cndmask_b32_e64 v3, v159, v175, s[6:7]
	v_cndmask_b32_e64 v4, v159, v175, s[8:9]
	v_cndmask_b32_e64 v5, v160, v176, s[8:9]
	v_mov_b32_dpp v155, v3 row_ror:1 row_mask:0xf bank_mask:0xf bound_ctrl:1
	v_mov_b32_dpp v3, v4 row_ror:2 row_mask:0xf bank_mask:0xf bound_ctrl:1
	v_cndmask_b32_e64 v4, v160, v176, s[6:7]
	v_pk_mul_f32 v[16:17], v[156:157], v[234:235] op_sel_hi:[1,0]
	v_cndmask_b32_e64 v6, v161, v177, s[8:9]
	v_mov_b32_dpp v156, v4 row_ror:1 row_mask:0xf bank_mask:0xf bound_ctrl:1
	v_mov_b32_dpp v4, v5 row_ror:2 row_mask:0xf bank_mask:0xf bound_ctrl:1
	v_cndmask_b32_e64 v5, v161, v177, s[6:7]
	v_cndmask_b32_e64 v7, v14, v170, s[8:9]
	v_cndmask_b32_e64 v8, v15, v171, s[8:9]
	v_mov_b32_dpp v157, v5 row_ror:1 row_mask:0xf bank_mask:0xf bound_ctrl:1
	v_mov_b32_dpp v5, v6 row_ror:2 row_mask:0xf bank_mask:0xf bound_ctrl:1
	v_cndmask_b32_e64 v6, v14, v170, s[6:7]
	v_cndmask_b32_e64 v9, v16, v172, s[8:9]
	v_cndmask_b32_e64 v162, v17, v173, s[8:9]
	v_mov_b32_dpp v10, v6 row_ror:1 row_mask:0xf bank_mask:0xf bound_ctrl:1
	v_mov_b32_dpp v6, v7 row_ror:2 row_mask:0xf bank_mask:0xf bound_ctrl:1
	v_cndmask_b32_e64 v7, v15, v171, s[6:7]
	s_andn2_b64 vcc, exec, s[90:91]
	s_nop 0
	v_mov_b32_dpp v11, v7 row_ror:1 row_mask:0xf bank_mask:0xf bound_ctrl:1
	v_mov_b32_dpp v7, v8 row_ror:2 row_mask:0xf bank_mask:0xf bound_ctrl:1
	v_cndmask_b32_e64 v8, v16, v172, s[6:7]
	s_nop 1
	v_mov_b32_dpp v12, v8 row_ror:1 row_mask:0xf bank_mask:0xf bound_ctrl:1
	v_mov_b32_dpp v8, v9 row_ror:2 row_mask:0xf bank_mask:0xf bound_ctrl:1
	v_cndmask_b32_e64 v9, v17, v173, s[6:7]
	s_nop 1
	v_mov_b32_dpp v13, v9 row_ror:1 row_mask:0xf bank_mask:0xf bound_ctrl:1
	v_cndmask_b32_e64 v9, 0, 1, s[90:91]
	v_cmp_ne_u32_e64 s[18:19], 1, v9
	s_nop 0
	v_mov_b32_dpp v9, v162 row_ror:2 row_mask:0xf bank_mask:0xf bound_ctrl:1
	s_cbranch_vccnz .LBB0_2679
	s_cbranch_execz .LBB0_2680
	s_branch .LBB0_2691

; __device__ __forceinline__ u32x4 pack8(f32x4 a, f32x4 b) { u32x4 w; w.x = cvt_pk_bf16(a[0], a[1]); w.y = cvt_pk_bf16(a[2], a[3]); w.z = cvt_pk_bf16(b[0], b[1]); w.w = cvt_pk_bf16(b[2], b[3]); return w; }
;     __device__ __forceinline__ void operator()(const f32x4 (&acc)[2][2][4][2], const Unit& u, int wr, int wc, int fr, int fq) const {
;     ...
;             for (int m = 0; m < 4; ++m) { const int row = row0 + ai * HALF + m * 16; const float s = sc8[ai][m];
;                 f32x4 zc[2], zp[2], vv[2], z1[2], z2[2];
; #pragma unroll
;                 for (int n = 0; n < 2; ++n) { zc[n] = acc[ai][0][m][n] * s; vv[n] = acc[ai][1][m][n] * s; zp[n] = zprev[n]; zprev[n] = zc[n]; }
; #pragma unroll
;                 for (int n = 0; n < 2; ++n)
; #pragma unroll
;                     for (int e = 0; e < 4; ++e) { const float t1 = fr == 15 ? zp[n][e] : zc[n][e], t2 = fr >= 14 ? zp[n][e] : zc[n][e];
;                         z1[n][e] = __builtin_bit_cast(float, __builtin_amdgcn_mov_dpp(__builtin_bit_cast(int, t1), 0x121, 0xf, 0xf, true));
;                         z2[n][e] = __builtin_bit_cast(float, __builtin_amdgcn_mov_dpp(__builtin_bit_cast(int, t2), 0x122, 0xf, 0xf, true)); }
;                 if (pm == 0) {
;                     if (fr < 2) { const float* st = stf + (size_t)(row >> 4) * 2 * DFF + col0;
; #pragma unroll
;                         for (int n = 0; n < 2; ++n) { const f32x4 b0 = *(const f32x4*)(st + 4 * n), b1 = *(const f32x4*)(st + DFF + 4 * n); if (fr == 0) { z1[n] = b1; z2[n] = b0; } else { z2[n] = b1; } } }
;                     const int s16 = row & 15;
;                     if (s16 >= 14) { float* dst = o_fcs + (size_t)((row >> 4) * 2 + (s16 - 14)) * DFF + col0; *(f32x4*)dst = zc[0]; *(f32x4*)(dst + 4) = zc[1]; }
;                 } else { const int t = row - G_ROWP; if (t >= G_TP - 2 && t < G_TP) { float* dst = o_fcp + (size_t)(t - (G_TP - 2)) * DFF + col0; *(f32x4*)dst = zc[0]; *(f32x4*)(dst + 4) = zc[1]; } }
;                 const bool defer = pm != 0 && m == 0 && fr < 2;
;                 if (!defer) { f32x4 a[2];
; #pragma unroll
;                     for (int n = 0; n < 2; ++n)
;                     { const f32x4 g = bb[n] + w0[n] * z2[n] + w1[n] * z1[n] + w2[n] * zc[n]; a[n] = gelu4(g) * vv[n]; }
;                     *(u32x4*)(ACT + (size_t)row * DFF + col0) = pack8(a[0], a[1]);
.LBB0_2690:
	s_or_b64 exec, exec, s[90:91]
	s_waitcnt vmcnt(0)
.LBB0_2691:
	v_pk_fma_f32 v[4:5], v[68:69], v[4:5], v[72:73]
	v_pk_fma_f32 v[2:3], v[66:67], v[2:3], v[70:71]
	v_pk_fma_f32 v[6:7], v[50:51], v[6:7], v[54:55]
	v_pk_fma_f32 v[4:5], v[64:65], v[156:157], v[4:5]
	v_pk_fma_f32 v[2:3], v[62:63], v[154:155], v[2:3]
	v_pk_fma_f32 v[6:7], v[46:47], v[10:11], v[6:7]
	v_mov_b32_e32 v162, v234
	v_mov_b32_e32 v163, v234
	v_pk_fma_f32 v[4:5], v[60:61], v[160:161], v[4:5]
	v_pk_fma_f32 v[2:3], v[58:59], v[158:159], v[2:3]
	v_pk_fma_f32 v[8:9], v[52:53], v[8:9], v[56:57]
	v_pk_fma_f32 v[6:7], v[42:43], v[14:15], v[6:7]
	v_pk_mul_f32 v[152:153], v[152:153], v[162:163]
	v_pk_mul_f32 v[148:149], v[148:149], v[162:163]
	v_pk_mul_f32 v[154:155], v[4:5], v[4:5]
	v_pk_mul_f32 v[156:157], v[2:3], v[2:3]
	v_mov_b64_e32 v[162:163], s[72:73]
	v_pk_fma_f32 v[8:9], v[48:49], v[12:13], v[8:9]
	v_pk_mul_f32 v[12:13], v[6:7], v[6:7]
	v_pk_fma_f32 v[154:155], v[154:155], s[74:75], v[162:163] op_sel_hi:[1,0,0] neg_lo:[1,0,0] neg_hi:[1,0,0]
	v_pk_fma_f32 v[156:157], v[156:157], s[74:75], v[162:163] op_sel_hi:[1,0,0] neg_lo:[1,0,0] neg_hi:[1,0,0]
	v_pk_fma_f32 v[8:9], v[44:45], v[16:17], v[8:9]
	v_pk_fma_f32 v[12:13], v[12:13], s[74:75], v[162:163] op_sel_hi:[1,0,0] neg_lo:[1,0,0] neg_hi:[1,0,0]
	v_pk_mul_f32 v[154:155], v[4:5], v[154:155]
	v_pk_mul_f32 v[156:157], v[2:3], v[156:157]
	v_pk_mul_f32 v[10:11], v[8:9], v[8:9]
	v_pk_mul_f32 v[12:13], v[6:7], v[12:13]
	v_exp_f32_e32 v156, v156
	v_exp_f32_e32 v157, v157
	v_exp_f32_e32 v154, v154
	v_exp_f32_e32 v155, v155
	v_pk_fma_f32 v[10:11], v[10:11], s[74:75], v[162:163] op_sel_hi:[1,0,0] neg_lo:[1,0,0] neg_hi:[1,0,0]
	v_exp_f32_e32 v12, v12
	v_exp_f32_e32 v13, v13
	v_pk_mul_f32 v[10:11], v[8:9], v[10:11]
	v_pk_add_f32 v[154:155], v[154:155], 1.0 op_sel_hi:[1,0]
	v_exp_f32_e32 v10, v10
	v_exp_f32_e32 v11, v11
	v_pk_add_f32 v[156:157], v[156:157], 1.0 op_sel_hi:[1,0]
	v_pk_add_f32 v[12:13], v[12:13], 1.0 op_sel_hi:[1,0]
	v_rcp_f32_e32 v156, v156
	v_rcp_f32_e32 v157, v157
	v_rcp_f32_e32 v154, v154
	v_rcp_f32_e32 v155, v155
	v_rcp_f32_e32 v12, v12
	v_rcp_f32_e32 v13, v13
	v_pk_add_f32 v[10:11], v[10:11], 1.0 op_sel_hi:[1,0]
	v_mov_b32_e32 v235, v234
	v_rcp_f32_e32 v10, v10
	v_rcp_f32_e32 v11, v11
	v_pk_mul_f32 v[150:151], v[150:151], v[234:235]
	v_pk_mul_f32 v[146:147], v[146:147], v[234:235]
	v_pk_mul_f32 v[4:5], v[4:5], v[154:155]
	v_pk_mul_f32 v[2:3], v[2:3], v[156:157]
	v_pk_mul_f32 v[6:7], v[6:7], v[12:13]
	v_pk_mul_f32 v[4:5], v[152:153], v[4:5]
	v_pk_mul_f32 v[2:3], v[150:151], v[2:3]
	v_pk_mul_f32 v[6:7], v[146:147], v[6:7]
	v_pk_mul_f32 v[8:9], v[8:9], v[10:11]
	v_cvt_pk_bf16_f32 v2, v2, v3
	v_cvt_pk_bf16_f32 v3, v4, v5
	v_cvt_pk_bf16_f32 v4, v6, v7
	v_mad_i64_i32 v[6:7], s[90:91], v232, s97, v[216:217]
	v_pk_mul_f32 v[142:143], v[142:143], v[230:231] op_sel_hi:[1,0]
	v_pk_mul_f32 v[8:9], v[148:149], v[8:9]
	v_pk_mul_f32 v[144:145], v[144:145], v[230:231] op_sel_hi:[1,0]
	v_cvt_pk_bf16_f32 v5, v8, v9
	global_store_dwordx4 v[6:7], v[2:5], off
	v_pk_mul_f32 v[10:11], v[138:139], v[230:231] op_sel_hi:[1,0]
	v_pk_mul_f32 v[12:13], v[140:141], v[230:231] op_sel_hi:[1,0]
	v_cndmask_b32_e64 v2, v142, v158, s[6:7]
	v_cndmask_b32_e64 v3, v142, v158, s[8:9]
	v_cndmask_b32_e64 v4, v143, v159, s[8:9]
	v_mov_b32_dpp v138, v2 row_ror:1 row_mask:0xf bank_mask:0xf bound_ctrl:1
	v_mov_b32_dpp v2, v3 row_ror:2 row_mask:0xf bank_mask:0xf bound_ctrl:1
	v_cndmask_b32_e64 v3, v143, v159, s[6:7]
	v_cndmask_b32_e64 v5, v144, v160, s[8:9]
	v_cndmask_b32_e64 v6, v145, v161, s[8:9]
	v_mov_b32_dpp v139, v3 row_ror:1 row_mask:0xf bank_mask:0xf bound_ctrl:1
	v_mov_b32_dpp v3, v4 row_ror:2 row_mask:0xf bank_mask:0xf bound_ctrl:1
	v_cndmask_b32_e64 v4, v144, v160, s[6:7]
	v_cndmask_b32_e64 v7, v10, v14, s[8:9]
	v_cndmask_b32_e64 v8, v11, v15, s[8:9]
	v_mov_b32_dpp v140, v4 row_ror:1 row_mask:0xf bank_mask:0xf bound_ctrl:1
	v_mov_b32_dpp v4, v5 row_ror:2 row_mask:0xf bank_mask:0xf bound_ctrl:1
	v_cndmask_b32_e64 v5, v145, v161, s[6:7]
	v_cndmask_b32_e64 v9, v12, v16, s[8:9]
	v_cndmask_b32_e64 v146, v13, v17, s[8:9]
	v_mov_b32_dpp v141, v5 row_ror:1 row_mask:0xf bank_mask:0xf bound_ctrl:1
	v_mov_b32_dpp v5, v6 row_ror:2 row_mask:0xf bank_mask:0xf bound_ctrl:1
	v_cndmask_b32_e64 v6, v10, v14, s[6:7]
	s_and_b64 vcc, exec, s[18:19]
	s_nop 0
	v_mov_b32_dpp v14, v6 row_ror:1 row_mask:0xf bank_mask:0xf bound_ctrl:1
	v_mov_b32_dpp v6, v7 row_ror:2 row_mask:0xf bank_mask:0xf bound_ctrl:1
	v_cndmask_b32_e64 v7, v11, v15, s[6:7]
	s_nop 1
	v_mov_b32_dpp v15, v7 row_ror:1 row_mask:0xf bank_mask:0xf bound_ctrl:1
	v_mov_b32_dpp v7, v8 row_ror:2 row_mask:0xf bank_mask:0xf bound_ctrl:1
	v_cndmask_b32_e64 v8, v12, v16, s[6:7]
	s_nop 1
	v_mov_b32_dpp v16, v8 row_ror:1 row_mask:0xf bank_mask:0xf bound_ctrl:1
	v_mov_b32_dpp v8, v9 row_ror:2 row_mask:0xf bank_mask:0xf bound_ctrl:1
	v_cndmask_b32_e64 v9, v13, v17, s[6:7]
	s_nop 1
	v_mov_b32_dpp v17, v9 row_ror:1 row_mask:0xf bank_mask:0xf bound_ctrl:1
	v_mov_b32_dpp v9, v146 row_ror:2 row_mask:0xf bank_mask:0xf bound_ctrl:1
	s_cbranch_vccnz .LBB0_2693
	s_cbranch_execz .LBB0_2694
	s_branch .LBB0_2705

; __device__ __forceinline__ u32x4 pack8(f32x4 a, f32x4 b) { u32x4 w; w.x = cvt_pk_bf16(a[0], a[1]); w.y = cvt_pk_bf16(a[2], a[3]); w.z = cvt_pk_bf16(b[0], b[1]); w.w = cvt_pk_bf16(b[2], b[3]); return w; }
;     __device__ __forceinline__ void operator()(const f32x4 (&acc)[2][2][4][2], const Unit& u, int wr, int wc, int fr, int fq) const {
;     ...
;             for (int m = 0; m < 4; ++m) { const int row = row0 + ai * HALF + m * 16; const float s = sc8[ai][m];
;                 f32x4 zc[2], zp[2], vv[2], z1[2], z2[2];
; #pragma unroll
;                 for (int n = 0; n < 2; ++n) { zc[n] = acc[ai][0][m][n] * s; vv[n] = acc[ai][1][m][n] * s; zp[n] = zprev[n]; zprev[n] = zc[n]; }
; #pragma unroll
;                 for (int n = 0; n < 2; ++n)
; #pragma unroll
;                     for (int e = 0; e < 4; ++e) { const float t1 = fr == 15 ? zp[n][e] : zc[n][e], t2 = fr >= 14 ? zp[n][e] : zc[n][e];
;                         z1[n][e] = __builtin_bit_cast(float, __builtin_amdgcn_mov_dpp(__builtin_bit_cast(int, t1), 0x121, 0xf, 0xf, true));
;                         z2[n][e] = __builtin_bit_cast(float, __builtin_amdgcn_mov_dpp(__builtin_bit_cast(int, t2), 0x122, 0xf, 0xf, true)); }
;                 if (pm == 0) {
;                     if (fr < 2) { const float* st = stf + (size_t)(row >> 4) * 2 * DFF + col0;
; #pragma unroll
;                         for (int n = 0; n < 2; ++n) { const f32x4 b0 = *(const f32x4*)(st + 4 * n), b1 = *(const f32x4*)(st + DFF + 4 * n); if (fr == 0) { z1[n] = b1; z2[n] = b0; } else { z2[n] = b1; } } }
;                     const int s16 = row & 15;
;                     if (s16 >= 14) { float* dst = o_fcs + (size_t)((row >> 4) * 2 + (s16 - 14)) * DFF + col0; *(f32x4*)dst = zc[0]; *(f32x4*)(dst + 4) = zc[1]; }
;                 } else { const int t = row - G_ROWP; if (t >= G_TP - 2 && t < G_TP) { float* dst = o_fcp + (size_t)(t - (G_TP - 2)) * DFF + col0; *(f32x4*)dst = zc[0]; *(f32x4*)(dst + 4) = zc[1]; } }
;                 const bool defer = pm != 0 && m == 0 && fr < 2;
;                 if (!defer) { f32x4 a[2];
; #pragma unroll
;                     for (int n = 0; n < 2; ++n)
;                     { const f32x4 g = bb[n] + w0[n] * z2[n] + w1[n] * z1[n] + w2[n] * zc[n]; a[n] = gelu4(g) * vv[n]; }
;                     *(u32x4*)(ACT + (size_t)row * DFF + col0) = pack8(a[0], a[1]);
.LBB0_2705:
	v_pk_fma_f32 v[4:5], v[68:69], v[4:5], v[72:73]
	v_pk_fma_f32 v[2:3], v[66:67], v[2:3], v[70:71]
	v_pk_fma_f32 v[6:7], v[50:51], v[6:7], v[54:55]
	v_pk_fma_f32 v[4:5], v[64:65], v[140:141], v[4:5]
	v_pk_fma_f32 v[2:3], v[62:63], v[138:139], v[2:3]
	v_pk_fma_f32 v[6:7], v[46:47], v[14:15], v[6:7]
	v_mov_b32_e32 v146, v230
	v_mov_b32_e32 v147, v230
	v_pk_fma_f32 v[4:5], v[60:61], v[144:145], v[4:5]
	v_pk_fma_f32 v[2:3], v[58:59], v[142:143], v[2:3]
	v_pk_fma_f32 v[8:9], v[52:53], v[8:9], v[56:57]
	v_pk_fma_f32 v[6:7], v[42:43], v[10:11], v[6:7]
	v_pk_mul_f32 v[136:137], v[136:137], v[146:147]
	v_pk_mul_f32 v[132:133], v[132:133], v[146:147]
	v_pk_mul_f32 v[138:139], v[4:5], v[4:5]
	v_pk_mul_f32 v[140:141], v[2:3], v[2:3]
	v_mov_b64_e32 v[146:147], s[72:73]
	v_pk_fma_f32 v[8:9], v[48:49], v[16:17], v[8:9]
	v_pk_mul_f32 v[16:17], v[6:7], v[6:7]
	v_pk_fma_f32 v[138:139], v[138:139], s[74:75], v[146:147] op_sel_hi:[1,0,0] neg_lo:[1,0,0] neg_hi:[1,0,0]
	v_pk_fma_f32 v[140:141], v[140:141], s[74:75], v[146:147] op_sel_hi:[1,0,0] neg_lo:[1,0,0] neg_hi:[1,0,0]
	v_pk_fma_f32 v[8:9], v[44:45], v[12:13], v[8:9]
	v_pk_fma_f32 v[16:17], v[16:17], s[74:75], v[146:147] op_sel_hi:[1,0,0] neg_lo:[1,0,0] neg_hi:[1,0,0]
	v_pk_mul_f32 v[138:139], v[4:5], v[138:139]
	v_pk_mul_f32 v[140:141], v[2:3], v[140:141]
	v_pk_mul_f32 v[14:15], v[8:9], v[8:9]
	v_pk_mul_f32 v[16:17], v[6:7], v[16:17]
	v_exp_f32_e32 v140, v140
	v_exp_f32_e32 v141, v141
	v_exp_f32_e32 v138, v138
	v_exp_f32_e32 v139, v139
	v_pk_fma_f32 v[14:15], v[14:15], s[74:75], v[146:147] op_sel_hi:[1,0,0] neg_lo:[1,0,0] neg_hi:[1,0,0]
	v_exp_f32_e32 v16, v16
	v_exp_f32_e32 v17, v17
	v_pk_mul_f32 v[14:15], v[8:9], v[14:15]
	v_pk_add_f32 v[138:139], v[138:139], 1.0 op_sel_hi:[1,0]
	v_exp_f32_e32 v14, v14
	v_exp_f32_e32 v15, v15
	v_pk_add_f32 v[140:141], v[140:141], 1.0 op_sel_hi:[1,0]
	v_pk_add_f32 v[16:17], v[16:17], 1.0 op_sel_hi:[1,0]
	v_rcp_f32_e32 v140, v140
	v_rcp_f32_e32 v141, v141
	v_rcp_f32_e32 v138, v138
	v_rcp_f32_e32 v139, v139
	v_rcp_f32_e32 v16, v16
	v_rcp_f32_e32 v17, v17
	v_pk_add_f32 v[14:15], v[14:15], 1.0 op_sel_hi:[1,0]
	v_mov_b32_e32 v231, v230
	v_rcp_f32_e32 v14, v14
	v_rcp_f32_e32 v15, v15
	v_pk_mul_f32 v[134:135], v[134:135], v[230:231]
	v_pk_mul_f32 v[130:131], v[130:131], v[230:231]
	v_pk_mul_f32 v[4:5], v[4:5], v[138:139]
	v_pk_mul_f32 v[2:3], v[2:3], v[140:141]
	v_pk_mul_f32 v[6:7], v[6:7], v[16:17]
	v_pk_mul_f32 v[4:5], v[136:137], v[4:5]
	v_pk_mul_f32 v[2:3], v[134:135], v[2:3]
	v_pk_mul_f32 v[6:7], v[130:131], v[6:7]
	v_pk_mul_f32 v[8:9], v[8:9], v[14:15]
	v_cvt_pk_bf16_f32 v2, v2, v3
	v_cvt_pk_bf16_f32 v3, v4, v5
	v_cvt_pk_bf16_f32 v4, v6, v7
	v_mad_i64_i32 v[6:7], s[90:91], v228, s97, v[216:217]
	v_pk_mul_f32 v[14:15], v[126:127], v[226:227] op_sel_hi:[1,0]
	v_pk_mul_f32 v[8:9], v[132:133], v[8:9]
	v_pk_mul_f32 v[16:17], v[128:129], v[226:227] op_sel_hi:[1,0]
	v_cvt_pk_bf16_f32 v5, v8, v9
	global_store_dwordx4 v[6:7], v[2:5], off
	v_pk_mul_f32 v[122:123], v[122:123], v[226:227] op_sel_hi:[1,0]
	v_cndmask_b32_e64 v6, v17, v145, s[8:9]
	v_cndmask_b32_e64 v2, v14, v142, s[6:7]
	v_cndmask_b32_e64 v3, v14, v142, s[8:9]
	v_cndmask_b32_e64 v4, v15, v143, s[8:9]
	v_mov_b32_dpp v126, v2 row_ror:1 row_mask:0xf bank_mask:0xf bound_ctrl:1
	v_mov_b32_dpp v2, v3 row_ror:2 row_mask:0xf bank_mask:0xf bound_ctrl:1
	v_cndmask_b32_e64 v3, v15, v143, s[6:7]
	v_cndmask_b32_e64 v5, v16, v144, s[8:9]
	v_cndmask_b32_e64 v7, v122, v10, s[8:9]
	v_mov_b32_dpp v127, v3 row_ror:1 row_mask:0xf bank_mask:0xf bound_ctrl:1
	v_mov_b32_dpp v3, v4 row_ror:2 row_mask:0xf bank_mask:0xf bound_ctrl:1
	v_cndmask_b32_e64 v4, v16, v144, s[6:7]
	v_pk_mul_f32 v[124:125], v[124:125], v[226:227] op_sel_hi:[1,0]
	v_cndmask_b32_e64 v8, v123, v11, s[8:9]
	v_mov_b32_dpp v128, v4 row_ror:1 row_mask:0xf bank_mask:0xf bound_ctrl:1
	v_mov_b32_dpp v4, v5 row_ror:2 row_mask:0xf bank_mask:0xf bound_ctrl:1
	v_cndmask_b32_e64 v5, v17, v145, s[6:7]
	v_cndmask_b32_e64 v9, v124, v12, s[8:9]
	v_cndmask_b32_e64 v130, v125, v13, s[8:9]
	v_mov_b32_dpp v129, v5 row_ror:1 row_mask:0xf bank_mask:0xf bound_ctrl:1
	v_mov_b32_dpp v5, v6 row_ror:2 row_mask:0xf bank_mask:0xf bound_ctrl:1
	v_cndmask_b32_e64 v6, v122, v10, s[6:7]
	s_and_b64 vcc, exec, s[18:19]
	s_nop 0
	v_mov_b32_dpp v10, v6 row_ror:1 row_mask:0xf bank_mask:0xf bound_ctrl:1
	v_mov_b32_dpp v6, v7 row_ror:2 row_mask:0xf bank_mask:0xf bound_ctrl:1
	v_cndmask_b32_e64 v7, v123, v11, s[6:7]
	s_nop 1
	v_mov_b32_dpp v11, v7 row_ror:1 row_mask:0xf bank_mask:0xf bound_ctrl:1
	v_mov_b32_dpp v7, v8 row_ror:2 row_mask:0xf bank_mask:0xf bound_ctrl:1
	v_cndmask_b32_e64 v8, v124, v12, s[6:7]
	s_nop 1
	v_mov_b32_dpp v12, v8 row_ror:1 row_mask:0xf bank_mask:0xf bound_ctrl:1
	v_mov_b32_dpp v8, v9 row_ror:2 row_mask:0xf bank_mask:0xf bound_ctrl:1
	v_cndmask_b32_e64 v9, v125, v13, s[6:7]
	s_nop 1
	v_mov_b32_dpp v13, v9 row_ror:1 row_mask:0xf bank_mask:0xf bound_ctrl:1
	v_mov_b32_dpp v9, v130 row_ror:2 row_mask:0xf bank_mask:0xf bound_ctrl:1
	s_cbranch_vccnz .LBB0_2707
	s_cbranch_execz .LBB0_2708
	s_branch .LBB0_2719

; __device__ __forceinline__ u32x4 pack8(f32x4 a, f32x4 b) { u32x4 w; w.x = cvt_pk_bf16(a[0], a[1]); w.y = cvt_pk_bf16(a[2], a[3]); w.z = cvt_pk_bf16(b[0], b[1]); w.w = cvt_pk_bf16(b[2], b[3]); return w; }
;     __device__ __forceinline__ void operator()(const f32x4 (&acc)[2][2][4][2], const Unit& u, int wr, int wc, int fr, int fq) const {
;     ...
;                 const bool defer = pm != 0 && m == 0 && fr < 2;
;                 if (!defer) { f32x4 a[2];
; #pragma unroll
;                     for (int n = 0; n < 2; ++n)
;                     { const f32x4 g = bb[n] + w0[n] * z2[n] + w1[n] * z1[n] + w2[n] * zc[n]; a[n] = gelu4(g) * vv[n]; }
;                     *(u32x4*)(ACT + (size_t)row * DFF + col0) = pack8(a[0], a[1]);
;                 } else { const size_t o = ((size_t)((row - G_ROWP) >> 6) * 2 + fr) * DFF + col0;
;                     *(f32x4*)(HEADG + o) = zc[0]; *(f32x4*)(HEADG + o + 4) = zc[1]; *(f32x4*)(HEADV + o) = vv[0]; *(f32x4*)(HEADV + o + 4) = vv[1]; }
;                 if (pm != 0 && m == 3 && fr >= 14) { const size_t o = ((size_t)((row - G_ROWP) >> 6) * 2 + (fr - 14)) * DFF + col0; *(f32x4*)(TAILG + o) = zc[0]; *(f32x4*)(TAILG + o + 4) = zc[1]; }
.LBB0_2719:
	v_pk_fma_f32 v[4:5], v[68:69], v[4:5], v[72:73]
	v_pk_fma_f32 v[2:3], v[66:67], v[2:3], v[70:71]
	v_pk_fma_f32 v[6:7], v[50:51], v[6:7], v[54:55]
	v_pk_fma_f32 v[4:5], v[64:65], v[128:129], v[4:5]
	v_pk_fma_f32 v[2:3], v[62:63], v[126:127], v[2:3]
	v_pk_fma_f32 v[6:7], v[46:47], v[10:11], v[6:7]
	v_pk_fma_f32 v[4:5], v[60:61], v[16:17], v[4:5]
	v_pk_fma_f32 v[2:3], v[58:59], v[14:15], v[2:3]
	v_pk_fma_f32 v[8:9], v[52:53], v[8:9], v[56:57]
	v_pk_fma_f32 v[6:7], v[42:43], v[122:123], v[6:7]
	v_pk_mul_f32 v[126:127], v[4:5], v[4:5]
	v_pk_mul_f32 v[128:129], v[2:3], v[2:3]
	v_mov_b64_e32 v[132:133], s[72:73]
	v_pk_fma_f32 v[8:9], v[48:49], v[12:13], v[8:9]
	v_pk_mul_f32 v[12:13], v[6:7], v[6:7]
	v_pk_fma_f32 v[126:127], v[126:127], s[74:75], v[132:133] op_sel_hi:[1,0,0] neg_lo:[1,0,0] neg_hi:[1,0,0]
	v_pk_fma_f32 v[128:129], v[128:129], s[74:75], v[132:133] op_sel_hi:[1,0,0] neg_lo:[1,0,0] neg_hi:[1,0,0]
	v_pk_fma_f32 v[8:9], v[44:45], v[124:125], v[8:9]
	v_pk_fma_f32 v[12:13], v[12:13], s[74:75], v[132:133] op_sel_hi:[1,0,0] neg_lo:[1,0,0] neg_hi:[1,0,0]
	v_pk_mul_f32 v[126:127], v[4:5], v[126:127]
	v_pk_mul_f32 v[128:129], v[2:3], v[128:129]
	v_pk_mul_f32 v[10:11], v[8:9], v[8:9]
	v_pk_mul_f32 v[12:13], v[6:7], v[12:13]
	v_exp_f32_e32 v128, v128
	v_exp_f32_e32 v129, v129
	v_exp_f32_e32 v126, v126
	v_exp_f32_e32 v127, v127
	v_pk_fma_f32 v[10:11], v[10:11], s[74:75], v[132:133] op_sel_hi:[1,0,0] neg_lo:[1,0,0] neg_hi:[1,0,0]
	v_exp_f32_e32 v12, v12
	v_exp_f32_e32 v13, v13
	v_pk_mul_f32 v[10:11], v[8:9], v[10:11]
	v_pk_add_f32 v[126:127], v[126:127], 1.0 op_sel_hi:[1,0]
	v_exp_f32_e32 v10, v10
	v_exp_f32_e32 v11, v11
	v_pk_add_f32 v[128:129], v[128:129], 1.0 op_sel_hi:[1,0]
	v_pk_add_f32 v[12:13], v[12:13], 1.0 op_sel_hi:[1,0]
	v_rcp_f32_e32 v128, v128
	v_rcp_f32_e32 v129, v129
	v_rcp_f32_e32 v126, v126
	v_rcp_f32_e32 v127, v127
	v_rcp_f32_e32 v12, v12
	v_rcp_f32_e32 v13, v13
	v_pk_add_f32 v[10:11], v[10:11], 1.0 op_sel_hi:[1,0]
	v_mov_b32_e32 v227, v226
	v_rcp_f32_e32 v10, v10
	v_rcp_f32_e32 v11, v11
	v_mov_b32_e32 v130, v226
	v_mov_b32_e32 v131, v226
	v_pk_mul_f32 v[120:121], v[120:121], v[130:131]
	v_pk_mul_f32 v[118:119], v[118:119], v[226:227]
	v_pk_mul_f32 v[116:117], v[116:117], v[130:131]
	v_pk_mul_f32 v[130:131], v[114:115], v[226:227]
	v_pk_mul_f32 v[4:5], v[4:5], v[126:127]
	v_pk_mul_f32 v[2:3], v[2:3], v[128:129]
	v_pk_mul_f32 v[6:7], v[6:7], v[12:13]
	v_pk_mul_f32 v[4:5], v[120:121], v[4:5]
	v_pk_mul_f32 v[2:3], v[118:119], v[2:3]
	v_pk_mul_f32 v[6:7], v[130:131], v[6:7]
	v_lshl_add_u64 v[114:115], v[212:213], 2, s[54:55]
	v_pk_mul_f32 v[8:9], v[8:9], v[10:11]
	v_cvt_pk_bf16_f32 v2, v2, v3
	v_cvt_pk_bf16_f32 v3, v4, v5
	v_cvt_pk_bf16_f32 v4, v6, v7
	v_mad_i64_i32 v[6:7], s[90:91], v224, s97, v[216:217]
	s_and_b64 s[86:87], s[86:87], s[8:9]
	v_pk_mul_f32 v[8:9], v[116:117], v[8:9]
	s_nop 0
	v_cvt_pk_bf16_f32 v5, v8, v9
	global_store_dwordx4 v[6:7], v[2:5], off
	s_and_saveexec_b64 s[90:91], s[86:87]
	s_cbranch_execz .LBB0_2721
	v_lshl_add_u64 v[2:3], s[88:89], 0, v[196:197]
	v_mad_u64_u32 v[4:5], s[88:89], v2, s0, v[114:115]
	v_mad_i32_i24 v5, v3, s0, v5
	global_store_dwordx4 v[4:5], v[14:17], off
	global_store_dwordx4 v[4:5], v[122:125], off offset:16

;     __device__ __forceinline__ void operator()(const f32x4 (&acc)[2][2][4][2], const Unit& u, int wr, int wc, int fr, int fq) const {
;     ...
;                 if (pm == 0) {
;                     if (fr < 2) { const float* st = stf + (size_t)(row >> 4) * 2 * DFF + col0;
; #pragma unroll
;                         for (int n = 0; n < 2; ++n) { const f32x4 b0 = *(const f32x4*)(st + 4 * n), b1 = *(const f32x4*)(st + DFF + 4 * n); if (fr == 0) { z1[n] = b1; z2[n] = b0; } else { z2[n] = b1; } } }
;                     const int s16 = row & 15;
;                     if (s16 >= 14) { float* dst = o_fcs + (size_t)((row >> 4) * 2 + (s16 - 14)) * DFF + col0; *(f32x4*)dst = zc[0]; *(f32x4*)(dst + 4) = zc[1]; }
.LBB0_2735:
	s_or_b64 exec, exec, s[90:91]
	s_waitcnt vmcnt(0)
	s_and_saveexec_b64 s[90:91], s[88:89]
	s_cbranch_execnz .LBB0_2738
	s_branch .LBB0_2739

; __device__ __forceinline__ u32x4 pack8(f32x4 a, f32x4 b) { u32x4 w; w.x = cvt_pk_bf16(a[0], a[1]); w.y = cvt_pk_bf16(a[2], a[3]); w.z = cvt_pk_bf16(b[0], b[1]); w.w = cvt_pk_bf16(b[2], b[3]); return w; }
;     __device__ __forceinline__ void operator()(const f32x4 (&acc)[2][2][4][2], const Unit& u, int wr, int wc, int fr, int fq) const {
;     ...
;                 const bool defer = pm != 0 && m == 0 && fr < 2;
;                 if (!defer) { f32x4 a[2];
; #pragma unroll
;                     for (int n = 0; n < 2; ++n)
;                     { const f32x4 g = bb[n] + w0[n] * z2[n] + w1[n] * z1[n] + w2[n] * zc[n]; a[n] = gelu4(g) * vv[n]; }
;                     *(u32x4*)(ACT + (size_t)row * DFF + col0) = pack8(a[0], a[1]);
.LBB0_2739:
	s_or_b64 exec, exec, s[90:91]
	v_mov_b32_e32 v223, v222
	v_mov_b32_e32 v116, v222
	v_mov_b32_e32 v117, v222
	v_pk_mul_f32 v[104:105], v[104:105], v[116:117]
	v_pk_mul_f32 v[102:103], v[102:103], v[222:223]
	v_pk_mul_f32 v[100:101], v[100:101], v[116:117]
	v_pk_mul_f32 v[98:99], v[98:99], v[222:223]
	s_and_saveexec_b64 s[88:89], s[84:85]
	s_xor_b64 s[84:85], exec, s[88:89]
	s_cbranch_execz .LBB0_2741
	v_pk_fma_f32 v[10:11], v[66:67], v[10:11], v[70:71]
	v_pk_fma_f32 v[12:13], v[68:69], v[12:13], v[72:73]
	v_pk_fma_f32 v[2:3], v[62:63], v[2:3], v[10:11]
	v_pk_fma_f32 v[4:5], v[64:65], v[4:5], v[12:13]
	v_pk_fma_f32 v[2:3], v[58:59], v[110:111], v[2:3]
	v_mov_b64_e32 v[116:117], s[72:73]
	v_pk_mul_f32 v[12:13], v[2:3], v[2:3]
	v_pk_fma_f32 v[4:5], v[60:61], v[112:113], v[4:5]
	v_pk_fma_f32 v[12:13], v[12:13], s[74:75], v[116:117] op_sel_hi:[1,0,0] neg_lo:[1,0,0] neg_hi:[1,0,0]
	v_pk_mul_f32 v[10:11], v[4:5], v[4:5]
	v_pk_mul_f32 v[12:13], v[2:3], v[12:13]
	v_pk_fma_f32 v[10:11], v[10:11], s[74:75], v[116:117] op_sel_hi:[1,0,0] neg_lo:[1,0,0] neg_hi:[1,0,0]
	v_exp_f32_e32 v12, v12
	v_exp_f32_e32 v13, v13
	v_pk_mul_f32 v[10:11], v[4:5], v[10:11]
	v_pk_add_f32 v[12:13], v[12:13], 1.0 op_sel_hi:[1,0]
	v_exp_f32_e32 v10, v10
	v_exp_f32_e32 v11, v11
	v_rcp_f32_e32 v12, v12
	v_rcp_f32_e32 v13, v13
	v_pk_add_f32 v[10:11], v[10:11], 1.0 op_sel_hi:[1,0]
	s_nop 0
	v_rcp_f32_e32 v10, v10
	v_rcp_f32_e32 v11, v11
	v_pk_mul_f32 v[2:3], v[2:3], v[12:13]
	v_pk_fma_f32 v[12:13], v[50:51], v[14:15], v[54:55]
	v_pk_mul_f32 v[2:3], v[102:103], v[2:3]
	v_pk_fma_f32 v[6:7], v[46:47], v[6:7], v[12:13]
	v_pk_mul_f32 v[4:5], v[4:5], v[10:11]
	v_pk_fma_f32 v[10:11], v[52:53], v[16:17], v[56:57]
	v_pk_fma_f32 v[6:7], v[42:43], v[106:107], v[6:7]
	v_pk_fma_f32 v[8:9], v[48:49], v[8:9], v[10:11]
	v_pk_mul_f32 v[12:13], v[6:7], v[6:7]
	v_pk_fma_f32 v[8:9], v[44:45], v[108:109], v[8:9]
	v_pk_fma_f32 v[12:13], v[12:13], s[74:75], v[116:117] op_sel_hi:[1,0,0] neg_lo:[1,0,0] neg_hi:[1,0,0]
	v_pk_mul_f32 v[10:11], v[8:9], v[8:9]
	v_pk_mul_f32 v[12:13], v[6:7], v[12:13]
	v_pk_fma_f32 v[10:11], v[10:11], s[74:75], v[116:117] op_sel_hi:[1,0,0] neg_lo:[1,0,0] neg_hi:[1,0,0]
	v_exp_f32_e32 v12, v12
	v_exp_f32_e32 v13, v13
	v_pk_mul_f32 v[10:11], v[8:9], v[10:11]
	v_pk_mul_f32 v[4:5], v[104:105], v[4:5]
	v_exp_f32_e32 v10, v10
	v_exp_f32_e32 v11, v11
	v_pk_add_f32 v[12:13], v[12:13], 1.0 op_sel_hi:[1,0]
	v_cvt_pk_bf16_f32 v2, v2, v3
	v_cvt_pk_bf16_f32 v3, v4, v5
	v_pk_add_f32 v[10:11], v[10:11], 1.0 op_sel_hi:[1,0]
	v_rcp_f32_e32 v12, v12
	v_rcp_f32_e32 v13, v13
	v_rcp_f32_e32 v10, v10
	v_rcp_f32_e32 v11, v11
	v_pk_mul_f32 v[6:7], v[6:7], v[12:13]
	s_nop 0
	v_pk_mul_f32 v[6:7], v[98:99], v[6:7]
	v_pk_mul_f32 v[8:9], v[8:9], v[10:11]
	v_cvt_pk_bf16_f32 v4, v6, v7
	v_mad_i64_i32 v[6:7], s[88:89], v118, s97, v[216:217]
	v_pk_mul_f32 v[8:9], v[100:101], v[8:9]
	s_nop 0
	v_cvt_pk_bf16_f32 v5, v8, v9
	global_store_dwordx4 v[6:7], v[2:5], off

;     __device__ __forceinline__ void operator()(const f32x4 (&acc)[2][2][4][2], const Unit& u, int wr, int wc, int fr, int fq) const {
;     ...
;                 for (int n = 0; n < 2; ++n) { zc[n] = acc[ai][0][m][n] * s; vv[n] = acc[ai][1][m][n] * s; zp[n] = zprev[n]; zprev[n] = zc[n]; }
; #pragma unroll
;                 for (int n = 0; n < 2; ++n)
; #pragma unroll
;                     for (int e = 0; e < 4; ++e) { const float t1 = fr == 15 ? zp[n][e] : zc[n][e], t2 = fr >= 14 ? zp[n][e] : zc[n][e];
;                         z1[n][e] = __builtin_bit_cast(float, __builtin_amdgcn_mov_dpp(__builtin_bit_cast(int, t1), 0x121, 0xf, 0xf, true));
;                         z2[n][e] = __builtin_bit_cast(float, __builtin_amdgcn_mov_dpp(__builtin_bit_cast(int, t2), 0x122, 0xf, 0xf, true)); }
.LBB0_2743:
	s_or_b64 exec, exec, s[88:89]
	v_pk_mul_f32 v[94:95], v[94:95], v[220:221] op_sel_hi:[1,0]
	v_pk_mul_f32 v[96:97], v[96:97], v[220:221] op_sel_hi:[1,0]
	v_cndmask_b32_e64 v2, v94, v110, s[6:7]
	v_cndmask_b32_e64 v3, v94, v110, s[8:9]
	v_pk_mul_f32 v[14:15], v[90:91], v[220:221] op_sel_hi:[1,0]
	v_mov_b32_dpp v90, v2 row_ror:1 row_mask:0xf bank_mask:0xf bound_ctrl:1
	v_mov_b32_dpp v2, v3 row_ror:2 row_mask:0xf bank_mask:0xf bound_ctrl:1
	v_cndmask_b32_e64 v3, v95, v111, s[6:7]
	v_cndmask_b32_e64 v4, v95, v111, s[8:9]
	v_cndmask_b32_e64 v5, v96, v112, s[8:9]
	v_mov_b32_dpp v91, v3 row_ror:1 row_mask:0xf bank_mask:0xf bound_ctrl:1
	v_mov_b32_dpp v3, v4 row_ror:2 row_mask:0xf bank_mask:0xf bound_ctrl:1
	v_cndmask_b32_e64 v4, v96, v112, s[6:7]
	v_pk_mul_f32 v[16:17], v[92:93], v[220:221] op_sel_hi:[1,0]
	v_cndmask_b32_e64 v6, v97, v113, s[8:9]
	v_mov_b32_dpp v92, v4 row_ror:1 row_mask:0xf bank_mask:0xf bound_ctrl:1
	v_mov_b32_dpp v4, v5 row_ror:2 row_mask:0xf bank_mask:0xf bound_ctrl:1
	v_cndmask_b32_e64 v5, v97, v113, s[6:7]
	v_cndmask_b32_e64 v7, v14, v106, s[8:9]
	v_cndmask_b32_e64 v8, v15, v107, s[8:9]
	v_mov_b32_dpp v93, v5 row_ror:1 row_mask:0xf bank_mask:0xf bound_ctrl:1
	v_mov_b32_dpp v5, v6 row_ror:2 row_mask:0xf bank_mask:0xf bound_ctrl:1
	v_cndmask_b32_e64 v6, v14, v106, s[6:7]
	v_cndmask_b32_e64 v9, v16, v108, s[8:9]
	v_cndmask_b32_e64 v98, v17, v109, s[8:9]
	v_mov_b32_dpp v10, v6 row_ror:1 row_mask:0xf bank_mask:0xf bound_ctrl:1
	v_mov_b32_dpp v6, v7 row_ror:2 row_mask:0xf bank_mask:0xf bound_ctrl:1
	v_cndmask_b32_e64 v7, v15, v107, s[6:7]
	s_and_b64 vcc, exec, s[18:19]
	s_nop 0
	v_mov_b32_dpp v11, v7 row_ror:1 row_mask:0xf bank_mask:0xf bound_ctrl:1
	v_mov_b32_dpp v7, v8 row_ror:2 row_mask:0xf bank_mask:0xf bound_ctrl:1
	v_cndmask_b32_e64 v8, v16, v108, s[6:7]
	s_nop 1
	v_mov_b32_dpp v12, v8 row_ror:1 row_mask:0xf bank_mask:0xf bound_ctrl:1
	v_mov_b32_dpp v8, v9 row_ror:2 row_mask:0xf bank_mask:0xf bound_ctrl:1
	v_cndmask_b32_e64 v9, v17, v109, s[6:7]
	s_nop 1
	v_mov_b32_dpp v13, v9 row_ror:1 row_mask:0xf bank_mask:0xf bound_ctrl:1
	v_mov_b32_dpp v9, v98 row_ror:2 row_mask:0xf bank_mask:0xf bound_ctrl:1
	s_cbranch_vccnz .LBB0_2745
	v_add_u32_e32 v100, 0x90, v214
	s_cbranch_execz .LBB0_2746
	s_branch .LBB0_2757

; __device__ __forceinline__ u32x4 pack8(f32x4 a, f32x4 b) { u32x4 w; w.x = cvt_pk_bf16(a[0], a[1]); w.y = cvt_pk_bf16(a[2], a[3]); w.z = cvt_pk_bf16(b[0], b[1]); w.w = cvt_pk_bf16(b[2], b[3]); return w; }
;     __device__ __forceinline__ void operator()(const f32x4 (&acc)[2][2][4][2], const Unit& u, int wr, int wc, int fr, int fq) const {
;     ...
;             for (int m = 0; m < 4; ++m) { const int row = row0 + ai * HALF + m * 16; const float s = sc8[ai][m];
;                 f32x4 zc[2], zp[2], vv[2], z1[2], z2[2];
; #pragma unroll
;                 for (int n = 0; n < 2; ++n) { zc[n] = acc[ai][0][m][n] * s; vv[n] = acc[ai][1][m][n] * s; zp[n] = zprev[n]; zprev[n] = zc[n]; }
; #pragma unroll
;                 for (int n = 0; n < 2; ++n)
; #pragma unroll
;                     for (int e = 0; e < 4; ++e) { const float t1 = fr == 15 ? zp[n][e] : zc[n][e], t2 = fr >= 14 ? zp[n][e] : zc[n][e];
;                         z1[n][e] = __builtin_bit_cast(float, __builtin_amdgcn_mov_dpp(__builtin_bit_cast(int, t1), 0x121, 0xf, 0xf, true));
;                         z2[n][e] = __builtin_bit_cast(float, __builtin_amdgcn_mov_dpp(__builtin_bit_cast(int, t2), 0x122, 0xf, 0xf, true)); }
;                 if (pm == 0) {
;                     if (fr < 2) { const float* st = stf + (size_t)(row >> 4) * 2 * DFF + col0;
; #pragma unroll
;                         for (int n = 0; n < 2; ++n) { const f32x4 b0 = *(const f32x4*)(st + 4 * n), b1 = *(const f32x4*)(st + DFF + 4 * n); if (fr == 0) { z1[n] = b1; z2[n] = b0; } else { z2[n] = b1; } } }
;                     const int s16 = row & 15;
;                     if (s16 >= 14) { float* dst = o_fcs + (size_t)((row >> 4) * 2 + (s16 - 14)) * DFF + col0; *(f32x4*)dst = zc[0]; *(f32x4*)(dst + 4) = zc[1]; }
;                 } else { const int t = row - G_ROWP; if (t >= G_TP - 2 && t < G_TP) { float* dst = o_fcp + (size_t)(t - (G_TP - 2)) * DFF + col0; *(f32x4*)dst = zc[0]; *(f32x4*)(dst + 4) = zc[1]; } }
;                 const bool defer = pm != 0 && m == 0 && fr < 2;
;                 if (!defer) { f32x4 a[2];
; #pragma unroll
;                     for (int n = 0; n < 2; ++n)
;                     { const f32x4 g = bb[n] + w0[n] * z2[n] + w1[n] * z1[n] + w2[n] * zc[n]; a[n] = gelu4(g) * vv[n]; }
;                     *(u32x4*)(ACT + (size_t)row * DFF + col0) = pack8(a[0], a[1]);
.LBB0_2754:
	s_or_b64 exec, exec, s[88:89]
	s_and_saveexec_b64 s[88:89], s[8:9]
	s_cbranch_execz .LBB0_2756
	v_ashrrev_i32_e32 v98, 3, v100
	v_and_b32_e32 v98, -6, v98
	v_add_u32_e32 v98, v98, v196
	v_mad_i64_i32 v[98:99], s[90:91], v98, s0, v[210:211]
	global_store_dwordx4 v[98:99], v[94:97], off
	global_store_dwordx4 v[98:99], v[14:17], off offset:16
.LBB0_2756:
	s_or_b64 exec, exec, s[88:89]
	s_waitcnt vmcnt(0)
.LBB0_2757:
	v_pk_fma_f32 v[4:5], v[68:69], v[4:5], v[72:73]
	v_pk_fma_f32 v[2:3], v[66:67], v[2:3], v[70:71]
	v_pk_fma_f32 v[6:7], v[50:51], v[6:7], v[54:55]
	v_pk_fma_f32 v[4:5], v[64:65], v[92:93], v[4:5]
	v_pk_fma_f32 v[2:3], v[62:63], v[90:91], v[2:3]
	v_pk_fma_f32 v[6:7], v[46:47], v[10:11], v[6:7]
	v_mov_b32_e32 v98, v220
	v_mov_b32_e32 v99, v220
	v_pk_fma_f32 v[4:5], v[60:61], v[96:97], v[4:5]
	v_pk_fma_f32 v[2:3], v[58:59], v[94:95], v[2:3]
	v_pk_fma_f32 v[8:9], v[52:53], v[8:9], v[56:57]
	v_pk_fma_f32 v[6:7], v[42:43], v[14:15], v[6:7]
	v_pk_mul_f32 v[88:89], v[88:89], v[98:99]
	v_pk_mul_f32 v[84:85], v[84:85], v[98:99]
	v_pk_mul_f32 v[90:91], v[4:5], v[4:5]
	v_pk_mul_f32 v[92:93], v[2:3], v[2:3]
	v_mov_b64_e32 v[98:99], s[72:73]
	v_pk_fma_f32 v[8:9], v[48:49], v[12:13], v[8:9]
	v_pk_mul_f32 v[12:13], v[6:7], v[6:7]
	v_pk_fma_f32 v[90:91], v[90:91], s[74:75], v[98:99] op_sel_hi:[1,0,0] neg_lo:[1,0,0] neg_hi:[1,0,0]
	v_pk_fma_f32 v[92:93], v[92:93], s[74:75], v[98:99] op_sel_hi:[1,0,0] neg_lo:[1,0,0] neg_hi:[1,0,0]
	v_pk_fma_f32 v[8:9], v[44:45], v[16:17], v[8:9]
	v_pk_fma_f32 v[12:13], v[12:13], s[74:75], v[98:99] op_sel_hi:[1,0,0] neg_lo:[1,0,0] neg_hi:[1,0,0]
	v_pk_mul_f32 v[90:91], v[4:5], v[90:91]
	v_pk_mul_f32 v[92:93], v[2:3], v[92:93]
	v_pk_mul_f32 v[10:11], v[8:9], v[8:9]
	v_pk_mul_f32 v[12:13], v[6:7], v[12:13]
	v_exp_f32_e32 v92, v92
	v_exp_f32_e32 v93, v93
	v_exp_f32_e32 v90, v90
	v_exp_f32_e32 v91, v91
	v_pk_fma_f32 v[10:11], v[10:11], s[74:75], v[98:99] op_sel_hi:[1,0,0] neg_lo:[1,0,0] neg_hi:[1,0,0]
	v_exp_f32_e32 v12, v12
	v_exp_f32_e32 v13, v13
	v_pk_mul_f32 v[10:11], v[8:9], v[10:11]
	v_pk_add_f32 v[90:91], v[90:91], 1.0 op_sel_hi:[1,0]
	v_exp_f32_e32 v10, v10
	v_exp_f32_e32 v11, v11
	v_pk_add_f32 v[92:93], v[92:93], 1.0 op_sel_hi:[1,0]
	v_pk_add_f32 v[12:13], v[12:13], 1.0 op_sel_hi:[1,0]
	v_rcp_f32_e32 v92, v92
	v_rcp_f32_e32 v93, v93
	v_rcp_f32_e32 v90, v90
	v_rcp_f32_e32 v91, v91
	v_rcp_f32_e32 v12, v12
	v_rcp_f32_e32 v13, v13
	v_pk_add_f32 v[10:11], v[10:11], 1.0 op_sel_hi:[1,0]
	v_mov_b32_e32 v221, v220
	v_rcp_f32_e32 v10, v10
	v_rcp_f32_e32 v11, v11
	v_pk_mul_f32 v[86:87], v[86:87], v[220:221]
	v_pk_mul_f32 v[82:83], v[82:83], v[220:221]
	v_pk_mul_f32 v[4:5], v[4:5], v[90:91]
	v_pk_mul_f32 v[2:3], v[2:3], v[92:93]
	v_pk_mul_f32 v[6:7], v[6:7], v[12:13]
	v_pk_mul_f32 v[4:5], v[88:89], v[4:5]
	v_pk_mul_f32 v[2:3], v[86:87], v[2:3]
	v_pk_mul_f32 v[6:7], v[82:83], v[6:7]
	v_pk_mul_f32 v[8:9], v[8:9], v[10:11]
	v_cvt_pk_bf16_f32 v2, v2, v3
	v_cvt_pk_bf16_f32 v3, v4, v5
	v_cvt_pk_bf16_f32 v4, v6, v7
	v_mad_i64_i32 v[6:7], s[88:89], v100, s97, v[216:217]
	v_pk_mul_f32 v[78:79], v[78:79], v[218:219] op_sel_hi:[1,0]
	v_pk_mul_f32 v[8:9], v[84:85], v[8:9]
	v_pk_mul_f32 v[80:81], v[80:81], v[218:219] op_sel_hi:[1,0]
	v_cvt_pk_bf16_f32 v5, v8, v9
	global_store_dwordx4 v[6:7], v[2:5], off
	v_pk_mul_f32 v[10:11], v[74:75], v[218:219] op_sel_hi:[1,0]
	v_pk_mul_f32 v[12:13], v[76:77], v[218:219] op_sel_hi:[1,0]
	v_cndmask_b32_e64 v2, v78, v94, s[6:7]
	v_cndmask_b32_e64 v3, v78, v94, s[8:9]
	v_cndmask_b32_e64 v4, v79, v95, s[8:9]
	v_mov_b32_dpp v74, v2 row_ror:1 row_mask:0xf bank_mask:0xf bound_ctrl:1
	v_mov_b32_dpp v2, v3 row_ror:2 row_mask:0xf bank_mask:0xf bound_ctrl:1
	v_cndmask_b32_e64 v3, v79, v95, s[6:7]
	v_cndmask_b32_e64 v5, v80, v96, s[8:9]
	v_cndmask_b32_e64 v6, v81, v97, s[8:9]
	v_mov_b32_dpp v75, v3 row_ror:1 row_mask:0xf bank_mask:0xf bound_ctrl:1
	v_mov_b32_dpp v3, v4 row_ror:2 row_mask:0xf bank_mask:0xf bound_ctrl:1
	v_cndmask_b32_e64 v4, v80, v96, s[6:7]
	v_cndmask_b32_e64 v7, v10, v14, s[8:9]
	v_cndmask_b32_e64 v8, v11, v15, s[8:9]
	v_mov_b32_dpp v76, v4 row_ror:1 row_mask:0xf bank_mask:0xf bound_ctrl:1
	v_mov_b32_dpp v4, v5 row_ror:2 row_mask:0xf bank_mask:0xf bound_ctrl:1
	v_cndmask_b32_e64 v5, v81, v97, s[6:7]
	v_cndmask_b32_e64 v9, v12, v16, s[8:9]
	v_cndmask_b32_e64 v82, v13, v17, s[8:9]
	v_mov_b32_dpp v77, v5 row_ror:1 row_mask:0xf bank_mask:0xf bound_ctrl:1
	v_mov_b32_dpp v5, v6 row_ror:2 row_mask:0xf bank_mask:0xf bound_ctrl:1
	v_cndmask_b32_e64 v6, v10, v14, s[6:7]
	s_and_b64 vcc, exec, s[18:19]
	s_nop 0
	v_mov_b32_dpp v14, v6 row_ror:1 row_mask:0xf bank_mask:0xf bound_ctrl:1
	v_mov_b32_dpp v6, v7 row_ror:2 row_mask:0xf bank_mask:0xf bound_ctrl:1
	v_cndmask_b32_e64 v7, v11, v15, s[6:7]
	s_nop 1
	v_mov_b32_dpp v15, v7 row_ror:1 row_mask:0xf bank_mask:0xf bound_ctrl:1
	v_mov_b32_dpp v7, v8 row_ror:2 row_mask:0xf bank_mask:0xf bound_ctrl:1
	v_cndmask_b32_e64 v8, v12, v16, s[6:7]
	s_nop 1
	v_mov_b32_dpp v16, v8 row_ror:1 row_mask:0xf bank_mask:0xf bound_ctrl:1
	v_mov_b32_dpp v8, v9 row_ror:2 row_mask:0xf bank_mask:0xf bound_ctrl:1
	v_cndmask_b32_e64 v9, v13, v17, s[6:7]
	s_nop 1
	v_mov_b32_dpp v17, v9 row_ror:1 row_mask:0xf bank_mask:0xf bound_ctrl:1
	v_mov_b32_dpp v9, v82 row_ror:2 row_mask:0xf bank_mask:0xf bound_ctrl:1
	s_cbranch_vccnz .LBB0_2759
	v_add_u32_e32 v84, 0xa0, v214
	s_cbranch_execz .LBB0_2760
	s_branch .LBB0_2771

; __device__ __forceinline__ u32x4 pack8(f32x4 a, f32x4 b) { u32x4 w; w.x = cvt_pk_bf16(a[0], a[1]); w.y = cvt_pk_bf16(a[2], a[3]); w.z = cvt_pk_bf16(b[0], b[1]); w.w = cvt_pk_bf16(b[2], b[3]); return w; }
;     __device__ __forceinline__ void operator()(const f32x4 (&acc)[2][2][4][2], const Unit& u, int wr, int wc, int fr, int fq) const {
;     ...
;             for (int m = 0; m < 4; ++m) { const int row = row0 + ai * HALF + m * 16; const float s = sc8[ai][m];
;                 f32x4 zc[2], zp[2], vv[2], z1[2], z2[2];
; #pragma unroll
;                 for (int n = 0; n < 2; ++n) { zc[n] = acc[ai][0][m][n] * s; vv[n] = acc[ai][1][m][n] * s; zp[n] = zprev[n]; zprev[n] = zc[n]; }
; #pragma unroll
;                 for (int n = 0; n < 2; ++n)
; #pragma unroll
;                     for (int e = 0; e < 4; ++e) { const float t1 = fr == 15 ? zp[n][e] : zc[n][e], t2 = fr >= 14 ? zp[n][e] : zc[n][e];
;                         z1[n][e] = __builtin_bit_cast(float, __builtin_amdgcn_mov_dpp(__builtin_bit_cast(int, t1), 0x121, 0xf, 0xf, true));
;                         z2[n][e] = __builtin_bit_cast(float, __builtin_amdgcn_mov_dpp(__builtin_bit_cast(int, t2), 0x122, 0xf, 0xf, true)); }
;                 if (pm == 0) {
;                     if (fr < 2) { const float* st = stf + (size_t)(row >> 4) * 2 * DFF + col0;
; #pragma unroll
;                         for (int n = 0; n < 2; ++n) { const f32x4 b0 = *(const f32x4*)(st + 4 * n), b1 = *(const f32x4*)(st + DFF + 4 * n); if (fr == 0) { z1[n] = b1; z2[n] = b0; } else { z2[n] = b1; } } }
;                     const int s16 = row & 15;
;                     if (s16 >= 14) { float* dst = o_fcs + (size_t)((row >> 4) * 2 + (s16 - 14)) * DFF + col0; *(f32x4*)dst = zc[0]; *(f32x4*)(dst + 4) = zc[1]; }
;                 } else { const int t = row - G_ROWP; if (t >= G_TP - 2 && t < G_TP) { float* dst = o_fcp + (size_t)(t - (G_TP - 2)) * DFF + col0; *(f32x4*)dst = zc[0]; *(f32x4*)(dst + 4) = zc[1]; } }
;                 const bool defer = pm != 0 && m == 0 && fr < 2;
;                 if (!defer) { f32x4 a[2];
; #pragma unroll
;                     for (int n = 0; n < 2; ++n)
;                     { const f32x4 g = bb[n] + w0[n] * z2[n] + w1[n] * z1[n] + w2[n] * zc[n]; a[n] = gelu4(g) * vv[n]; }
;                     *(u32x4*)(ACT + (size_t)row * DFF + col0) = pack8(a[0], a[1]);
.LBB0_2768:
	s_or_b64 exec, exec, s[88:89]
	s_and_saveexec_b64 s[88:89], s[8:9]
	s_cbranch_execz .LBB0_2770
	v_ashrrev_i32_e32 v82, 3, v84
	v_and_b32_e32 v82, -4, v82
	v_add_u32_e32 v82, v82, v196
	v_mad_i64_i32 v[82:83], s[90:91], v82, s0, v[210:211]
	global_store_dwordx4 v[82:83], v[78:81], off
	global_store_dwordx4 v[82:83], v[10:13], off offset:16
.LBB0_2770:
	s_or_b64 exec, exec, s[88:89]
	s_waitcnt vmcnt(0)
.LBB0_2771:
	v_pk_fma_f32 v[4:5], v[68:69], v[4:5], v[72:73]
	v_pk_fma_f32 v[2:3], v[66:67], v[2:3], v[70:71]
	v_pk_fma_f32 v[6:7], v[50:51], v[6:7], v[54:55]
	v_pk_fma_f32 v[4:5], v[64:65], v[76:77], v[4:5]
	v_pk_fma_f32 v[2:3], v[62:63], v[74:75], v[2:3]
	v_pk_fma_f32 v[6:7], v[46:47], v[14:15], v[6:7]
	v_mov_b32_e32 v82, v218
	v_mov_b32_e32 v83, v218
	v_pk_fma_f32 v[4:5], v[60:61], v[80:81], v[4:5]
	v_pk_fma_f32 v[2:3], v[58:59], v[78:79], v[2:3]
	v_pk_fma_f32 v[8:9], v[52:53], v[8:9], v[56:57]
	v_pk_fma_f32 v[6:7], v[42:43], v[10:11], v[6:7]
	v_pk_mul_f32 v[40:41], v[40:41], v[82:83]
	v_pk_mul_f32 v[36:37], v[36:37], v[82:83]
	v_pk_mul_f32 v[74:75], v[4:5], v[4:5]
	v_pk_mul_f32 v[76:77], v[2:3], v[2:3]
	v_mov_b64_e32 v[82:83], s[72:73]
	v_pk_fma_f32 v[8:9], v[48:49], v[16:17], v[8:9]
	v_pk_mul_f32 v[16:17], v[6:7], v[6:7]
	v_pk_fma_f32 v[74:75], v[74:75], s[74:75], v[82:83] op_sel_hi:[1,0,0] neg_lo:[1,0,0] neg_hi:[1,0,0]
	v_pk_fma_f32 v[76:77], v[76:77], s[74:75], v[82:83] op_sel_hi:[1,0,0] neg_lo:[1,0,0] neg_hi:[1,0,0]
	v_pk_fma_f32 v[8:9], v[44:45], v[12:13], v[8:9]
	v_pk_fma_f32 v[16:17], v[16:17], s[74:75], v[82:83] op_sel_hi:[1,0,0] neg_lo:[1,0,0] neg_hi:[1,0,0]
	v_pk_mul_f32 v[74:75], v[4:5], v[74:75]
	v_pk_mul_f32 v[76:77], v[2:3], v[76:77]
	v_pk_mul_f32 v[14:15], v[8:9], v[8:9]
	v_pk_mul_f32 v[16:17], v[6:7], v[16:17]
	v_exp_f32_e32 v76, v76
	v_exp_f32_e32 v77, v77
	v_exp_f32_e32 v74, v74
	v_exp_f32_e32 v75, v75
	v_pk_fma_f32 v[14:15], v[14:15], s[74:75], v[82:83] op_sel_hi:[1,0,0] neg_lo:[1,0,0] neg_hi:[1,0,0]
	v_exp_f32_e32 v16, v16
	v_exp_f32_e32 v17, v17
	v_pk_mul_f32 v[14:15], v[8:9], v[14:15]
	v_pk_add_f32 v[74:75], v[74:75], 1.0 op_sel_hi:[1,0]
	v_exp_f32_e32 v14, v14
	v_exp_f32_e32 v15, v15
	v_pk_add_f32 v[76:77], v[76:77], 1.0 op_sel_hi:[1,0]
	v_pk_add_f32 v[16:17], v[16:17], 1.0 op_sel_hi:[1,0]
	v_rcp_f32_e32 v76, v76
	v_rcp_f32_e32 v77, v77
	v_rcp_f32_e32 v74, v74
	v_rcp_f32_e32 v75, v75
	v_rcp_f32_e32 v16, v16
	v_rcp_f32_e32 v17, v17
	v_pk_add_f32 v[14:15], v[14:15], 1.0 op_sel_hi:[1,0]
	v_mov_b32_e32 v219, v218
	v_rcp_f32_e32 v14, v14
	v_rcp_f32_e32 v15, v15
	v_pk_mul_f32 v[38:39], v[38:39], v[218:219]
	v_pk_mul_f32 v[34:35], v[34:35], v[218:219]
	v_pk_mul_f32 v[4:5], v[4:5], v[74:75]
	v_pk_mul_f32 v[2:3], v[2:3], v[76:77]
	v_pk_mul_f32 v[6:7], v[6:7], v[16:17]
	v_pk_mul_f32 v[4:5], v[40:41], v[4:5]
	v_pk_mul_f32 v[2:3], v[38:39], v[2:3]
	v_pk_mul_f32 v[6:7], v[34:35], v[6:7]
	v_pk_mul_f32 v[8:9], v[8:9], v[14:15]
	v_cvt_pk_bf16_f32 v2, v2, v3
	v_cvt_pk_bf16_f32 v3, v4, v5
	v_cvt_pk_bf16_f32 v4, v6, v7
	v_mad_i64_i32 v[6:7], s[88:89], v84, s97, v[216:217]
	v_pk_mul_f32 v[14:15], v[30:31], v[208:209] op_sel_hi:[1,0]
	v_pk_mul_f32 v[8:9], v[36:37], v[8:9]
	v_pk_mul_f32 v[16:17], v[32:33], v[208:209] op_sel_hi:[1,0]
	v_cvt_pk_bf16_f32 v5, v8, v9
	global_store_dwordx4 v[6:7], v[2:5], off
	v_pk_mul_f32 v[26:27], v[26:27], v[208:209] op_sel_hi:[1,0]
	v_cndmask_b32_e64 v6, v17, v81, s[8:9]
	v_cndmask_b32_e64 v2, v14, v78, s[6:7]
	v_cndmask_b32_e64 v3, v14, v78, s[8:9]
	v_cndmask_b32_e64 v4, v15, v79, s[8:9]
	v_mov_b32_dpp v30, v2 row_ror:1 row_mask:0xf bank_mask:0xf bound_ctrl:1
	v_mov_b32_dpp v2, v3 row_ror:2 row_mask:0xf bank_mask:0xf bound_ctrl:1
	v_cndmask_b32_e64 v3, v15, v79, s[6:7]
	v_cndmask_b32_e64 v5, v16, v80, s[8:9]
	v_cndmask_b32_e64 v7, v26, v10, s[8:9]
	v_mov_b32_dpp v31, v3 row_ror:1 row_mask:0xf bank_mask:0xf bound_ctrl:1
	v_mov_b32_dpp v3, v4 row_ror:2 row_mask:0xf bank_mask:0xf bound_ctrl:1
	v_cndmask_b32_e64 v4, v16, v80, s[6:7]
	v_pk_mul_f32 v[28:29], v[28:29], v[208:209] op_sel_hi:[1,0]
	v_cndmask_b32_e64 v8, v27, v11, s[8:9]
	v_mov_b32_dpp v32, v4 row_ror:1 row_mask:0xf bank_mask:0xf bound_ctrl:1
	v_mov_b32_dpp v4, v5 row_ror:2 row_mask:0xf bank_mask:0xf bound_ctrl:1
	v_cndmask_b32_e64 v5, v17, v81, s[6:7]
	v_cndmask_b32_e64 v9, v28, v12, s[8:9]
	v_cndmask_b32_e64 v34, v29, v13, s[8:9]
	v_mov_b32_dpp v33, v5 row_ror:1 row_mask:0xf bank_mask:0xf bound_ctrl:1
	v_mov_b32_dpp v5, v6 row_ror:2 row_mask:0xf bank_mask:0xf bound_ctrl:1
	v_cndmask_b32_e64 v6, v26, v10, s[6:7]
	s_and_b64 vcc, exec, s[18:19]
	s_nop 0
	v_mov_b32_dpp v10, v6 row_ror:1 row_mask:0xf bank_mask:0xf bound_ctrl:1
	v_mov_b32_dpp v6, v7 row_ror:2 row_mask:0xf bank_mask:0xf bound_ctrl:1
	v_cndmask_b32_e64 v7, v27, v11, s[6:7]
	s_nop 1
	v_mov_b32_dpp v11, v7 row_ror:1 row_mask:0xf bank_mask:0xf bound_ctrl:1
	v_mov_b32_dpp v7, v8 row_ror:2 row_mask:0xf bank_mask:0xf bound_ctrl:1
	v_cndmask_b32_e64 v8, v28, v12, s[6:7]
	s_nop 1
	v_mov_b32_dpp v12, v8 row_ror:1 row_mask:0xf bank_mask:0xf bound_ctrl:1
	v_mov_b32_dpp v8, v9 row_ror:2 row_mask:0xf bank_mask:0xf bound_ctrl:1
	v_cndmask_b32_e64 v9, v29, v13, s[6:7]
	s_nop 1
	v_mov_b32_dpp v13, v9 row_ror:1 row_mask:0xf bank_mask:0xf bound_ctrl:1
	v_mov_b32_dpp v9, v34 row_ror:2 row_mask:0xf bank_mask:0xf bound_ctrl:1
	s_cbranch_vccnz .LBB0_2773
	v_add_u32_e32 v36, 0xb0, v214
	s_cbranch_execz .LBB0_2774
	s_branch .LBB0_2779

; __device__ __forceinline__ u32x4 pack8(f32x4 a, f32x4 b) { u32x4 w; w.x = cvt_pk_bf16(a[0], a[1]); w.y = cvt_pk_bf16(a[2], a[3]); w.z = cvt_pk_bf16(b[0], b[1]); w.w = cvt_pk_bf16(b[2], b[3]); return w; }
;     __device__ __forceinline__ void operator()(const f32x4 (&acc)[2][2][4][2], const Unit& u, int wr, int wc, int fr, int fq) const {
;     ...
;                 const bool defer = pm != 0 && m == 0 && fr < 2;
;                 if (!defer) { f32x4 a[2];
; #pragma unroll
;                     for (int n = 0; n < 2; ++n)
;                     { const f32x4 g = bb[n] + w0[n] * z2[n] + w1[n] * z1[n] + w2[n] * zc[n]; a[n] = gelu4(g) * vv[n]; }
;                     *(u32x4*)(ACT + (size_t)row * DFF + col0) = pack8(a[0], a[1]);
;                 } else { const size_t o = ((size_t)((row - G_ROWP) >> 6) * 2 + fr) * DFF + col0;
;                     *(f32x4*)(HEADG + o) = zc[0]; *(f32x4*)(HEADG + o + 4) = zc[1]; *(f32x4*)(HEADV + o) = vv[0]; *(f32x4*)(HEADV + o + 4) = vv[1]; }
;                 if (pm != 0 && m == 3 && fr >= 14) { const size_t o = ((size_t)((row - G_ROWP) >> 6) * 2 + (fr - 14)) * DFF + col0; *(f32x4*)(TAILG + o) = zc[0]; *(f32x4*)(TAILG + o + 4) = zc[1]; }
.LBB0_2778:
	s_or_b64 exec, exec, s[18:19]
	s_waitcnt vmcnt(0)
.LBB0_2779:
	v_pk_fma_f32 v[4:5], v[68:69], v[4:5], v[72:73]
	v_pk_fma_f32 v[2:3], v[66:67], v[2:3], v[70:71]
	v_pk_fma_f32 v[6:7], v[50:51], v[6:7], v[54:55]
	v_pk_fma_f32 v[4:5], v[64:65], v[32:33], v[4:5]
	v_pk_fma_f32 v[2:3], v[62:63], v[30:31], v[2:3]
	v_pk_fma_f32 v[6:7], v[46:47], v[10:11], v[6:7]
	v_pk_fma_f32 v[4:5], v[60:61], v[16:17], v[4:5]
	v_pk_fma_f32 v[2:3], v[58:59], v[14:15], v[2:3]
	v_pk_fma_f32 v[8:9], v[52:53], v[8:9], v[56:57]
	v_pk_fma_f32 v[6:7], v[42:43], v[26:27], v[6:7]
	v_pk_mul_f32 v[30:31], v[4:5], v[4:5]
	v_pk_mul_f32 v[32:33], v[2:3], v[2:3]
	v_mov_b64_e32 v[38:39], s[72:73]
	v_pk_fma_f32 v[8:9], v[48:49], v[12:13], v[8:9]
	v_pk_mul_f32 v[12:13], v[6:7], v[6:7]
	v_pk_fma_f32 v[30:31], v[30:31], s[74:75], v[38:39] op_sel_hi:[1,0,0] neg_lo:[1,0,0] neg_hi:[1,0,0]
	v_pk_fma_f32 v[32:33], v[32:33], s[74:75], v[38:39] op_sel_hi:[1,0,0] neg_lo:[1,0,0] neg_hi:[1,0,0]
	v_pk_fma_f32 v[8:9], v[44:45], v[28:29], v[8:9]
	v_pk_fma_f32 v[12:13], v[12:13], s[74:75], v[38:39] op_sel_hi:[1,0,0] neg_lo:[1,0,0] neg_hi:[1,0,0]
	v_pk_mul_f32 v[30:31], v[4:5], v[30:31]
	v_pk_mul_f32 v[32:33], v[2:3], v[32:33]
	v_pk_mul_f32 v[10:11], v[8:9], v[8:9]
	v_pk_mul_f32 v[12:13], v[6:7], v[12:13]
	v_exp_f32_e32 v32, v32
	v_exp_f32_e32 v30, v30
	v_exp_f32_e32 v31, v31
	v_exp_f32_e32 v33, v33
	v_pk_fma_f32 v[10:11], v[10:11], s[74:75], v[38:39] op_sel_hi:[1,0,0] neg_lo:[1,0,0] neg_hi:[1,0,0]
	v_exp_f32_e32 v12, v12
	v_exp_f32_e32 v13, v13
	v_pk_mul_f32 v[10:11], v[8:9], v[10:11]
	v_pk_add_f32 v[30:31], v[30:31], 1.0 op_sel_hi:[1,0]
	v_exp_f32_e32 v10, v10
	v_exp_f32_e32 v11, v11
	v_pk_add_f32 v[32:33], v[32:33], 1.0 op_sel_hi:[1,0]
	v_pk_add_f32 v[12:13], v[12:13], 1.0 op_sel_hi:[1,0]
	v_rcp_f32_e32 v32, v32
	v_rcp_f32_e32 v33, v33
	v_rcp_f32_e32 v30, v30
	v_rcp_f32_e32 v31, v31
	v_rcp_f32_e32 v12, v12
	v_rcp_f32_e32 v13, v13
	v_pk_add_f32 v[10:11], v[10:11], 1.0 op_sel_hi:[1,0]
	v_mov_b32_e32 v209, v208
	v_rcp_f32_e32 v10, v10
	v_rcp_f32_e32 v11, v11
	v_mov_b32_e32 v34, v208
	v_mov_b32_e32 v35, v208
	v_pk_mul_f32 v[24:25], v[24:25], v[34:35]
	v_pk_mul_f32 v[22:23], v[22:23], v[208:209]
	v_pk_mul_f32 v[18:19], v[18:19], v[208:209]
	v_pk_mul_f32 v[4:5], v[4:5], v[30:31]
	v_pk_mul_f32 v[2:3], v[2:3], v[32:33]
	v_pk_mul_f32 v[6:7], v[6:7], v[12:13]
	v_pk_mul_f32 v[4:5], v[24:25], v[4:5]
	v_pk_mul_f32 v[2:3], v[22:23], v[2:3]
	v_pk_mul_f32 v[6:7], v[18:19], v[6:7]
	v_pk_mul_f32 v[20:21], v[20:21], v[34:35]
	v_pk_mul_f32 v[8:9], v[8:9], v[10:11]
	v_cvt_pk_bf16_f32 v2, v2, v3
	v_cvt_pk_bf16_f32 v3, v4, v5
	v_cvt_pk_bf16_f32 v4, v6, v7
	v_mad_i64_i32 v[6:7], s[18:19], v36, s97, v[216:217]
	v_pk_mul_f32 v[8:9], v[20:21], v[8:9]
	s_nop 0
	v_cvt_pk_bf16_f32 v5, v8, v9
	global_store_dwordx4 v[6:7], v[2:5], off
	s_and_saveexec_b64 s[18:19], s[86:87]
	s_cbranch_execz .LBB0_2781
	v_lshl_add_u64 v[2:3], s[84:85], 0, v[196:197]
	v_mad_u64_u32 v[4:5], s[84:85], v2, s0, v[114:115]
	v_mad_i32_i24 v5, v3, s0, v5
	global_store_dwordx4 v[4:5], v[14:17], off
	global_store_dwordx4 v[4:5], v[26:29], off offset:16

; __global__ void __launch_bounds__(NTHR, 2) fwd_kernel(Args args) {
	.amdhsa_kernel _Z10fwd_kernel4Args
		.amdhsa_group_segment_fixed_size 0
		.amdhsa_private_segment_fixed_size 0
		.amdhsa_kernarg_size 496
		.amdhsa_user_sgpr_count 2
		.amdhsa_user_sgpr_dispatch_ptr 0
		.amdhsa_user_sgpr_queue_ptr 0
		.amdhsa_user_sgpr_kernarg_segment_ptr 1
		.amdhsa_user_sgpr_dispatch_id 0
		.amdhsa_user_sgpr_kernarg_preload_length 0
		.amdhsa_user_sgpr_kernarg_preload_offset 0
		.amdhsa_user_sgpr_private_segment_size 0
		.amdhsa_uses_dynamic_stack 0
		.amdhsa_enable_private_segment 0
		.amdhsa_system_sgpr_workgroup_id_x 1
		.amdhsa_system_sgpr_workgroup_id_y 0
		.amdhsa_system_sgpr_workgroup_id_z 0
		.amdhsa_system_sgpr_workgroup_info 0
		.amdhsa_system_vgpr_workitem_id 0
		.amdhsa_next_free_vgpr 256
		.amdhsa_next_free_sgpr 102
		.amdhsa_accum_offset 256
		.amdhsa_reserve_vcc 1
		.amdhsa_float_round_mode_32 0
		.amdhsa_float_round_mode_16_64 0
		.amdhsa_float_denorm_mode_32 3
		.amdhsa_float_denorm_mode_16_64 3
		.amdhsa_dx10_clamp 1
		.amdhsa_ieee_mode 1
		.amdhsa_fp16_overflow 0
		.amdhsa_tg_split 0
		.amdhsa_exception_fp_ieee_invalid_op 0
		.amdhsa_exception_fp_denorm_src 0
		.amdhsa_exception_fp_ieee_div_zero 0
		.amdhsa_exception_fp_ieee_overflow 0
		.amdhsa_exception_fp_ieee_underflow 0
		.amdhsa_exception_fp_ieee_inexact 0
		.amdhsa_exception_int_div_zero 0
	.end_amdhsa_kernel

; __global__ void __launch_bounds__(NTHR, 2) fwd_kernel(Args args) {
amdhsa.kernels:
  - .agpr_count:     0
    .args:
      - .offset:         0
        .size:           240
        .value_kind:     by_value
      - .offset:         240
        .size:           4
        .value_kind:     hidden_block_count_x
      - .offset:         244
        .size:           4
        .value_kind:     hidden_block_count_y
      - .offset:         248
        .size:           4
        .value_kind:     hidden_block_count_z
      - .offset:         252
        .size:           2
        .value_kind:     hidden_group_size_x
      - .offset:         254
        .size:           2
        .value_kind:     hidden_group_size_y
      - .offset:         256
        .size:           2
        .value_kind:     hidden_group_size_z
      - .offset:         258
        .size:           2
        .value_kind:     hidden_remainder_x
      - .offset:         260
        .size:           2
        .value_kind:     hidden_remainder_y
      - .offset:         262
        .size:           2
        .value_kind:     hidden_remainder_z
      - .offset:         280
        .size:           8
        .value_kind:     hidden_global_offset_x
      - .offset:         288
        .size:           8
        .value_kind:     hidden_global_offset_y
      - .offset:         296
        .size:           8
        .value_kind:     hidden_global_offset_z
      - .offset:         304
        .size:           2
        .value_kind:     hidden_grid_dims
      - .offset:         360
        .size:           4
        .value_kind:     hidden_dynamic_lds_size
    .group_segment_fixed_size: 0
    .kernarg_segment_align: 8
    .kernarg_segment_size: 496
    .language:       OpenCL C
    .language_version:
      - 2
      - 0
    .max_flat_workgroup_size: 512
    .name:           _Z10fwd_kernel4Args
    .private_segment_fixed_size: 0
    .sgpr_count:     108
    .sgpr_spill_count: 20
    .symbol:         _Z10fwd_kernel4Args.kd
    .uniform_work_group_size: 1
    .uses_dynamic_stack: false
    .vgpr_count:     256
    .vgpr_spill_count: 0
    .wavefront_size: 64
